# GEMM k-loops: MFMAs ordered in B-fragment pairs with reads A0,B0,A1,B1.. so later fragments are needed later; attention LDS prefetch ring reduced to 4 slots
# baseline (speedup 1.0000x reference)
; DI int opaque_tid() { int t = threadIdx.x; asm volatile("" : "+v"(t)); return t; }
; DI f32x16 zero16() { f32x16 z; for (int i = 0; i < 16; ++i) z[i] = 0.f; return z; }
; #define GEMM_ISSUE(KT, ST) do { const int k1_ = (KT) << 6; unsigned char* d_ = ldst + (ST) * STAGE; \
;         _Pragma("unroll") for (int j_ = 0; j_ < 4; ++j_) dma16(ap + (size_t)(64 * j_) * lda + k1_, d_ + j_ * 8192); \
;         _Pragma("unroll") for (int j_ = 0; j_ < NBW; ++j_) dma16(bp + bro[j_] + k1_, d_ + BOFF + j_ * 8192); } while (0)
; template <int NBW>
; DI void gemm_mainloop(f32x16 (&acc)[2][NBW], const bf16_t* A, size_t lda, int m0, const bf16_t* Bt, size_t ldb, int n0, int K, unsigned char* lds, bool pre = false, bool only_issue = false) {
;     ...
;     const int t = opaque_tid(), w = t >> 6, lane = t & 63, r = lane & 31, hh = lane >> 5, wm = w >> 1, wn = w & 1;
;     const int drow = w * 8 + (lane >> 3);
;     const int lchunk = (lane & 7) ^ ((drow >> 1) & 7);
;     const bf16_t* ap = A + (size_t)(m0 + drow) * lda + lchunk * 8;
;     const bf16_t* bp = Bt + (size_t)n0 * ldb + lchunk * 8;
;     size_t bro[NBW];
; #pragma unroll
;     for (int j = 0; j < NBW; ++j) {
;         const int rho = 64 * j + drow; const int wnh = rho / (32 * NBW), wi = rho % (32 * NBW);
;         bro[j] = (size_t)(wnh * 32 * NBW + NBW * (wi & 31) + (wi >> 5)) * ldb;
;     }
;     unsigned char* ldst = lds + w * 1024 + lane * 16;
;     ...
;     if (!pre) GEMM_ISSUE(0, 0);
;     if (only_issue) return;
;     __syncthreads();
;     const int nk = K >> 6;
;     const int xr = (r >> 1) & 7;
;     int xo[4];
; #pragma unroll
;     for (int s = 0; s < 4; ++s) xo[s] = ((2 * s + hh) ^ xr) << 4;
;     const int aofs = (wm * 64 + r) * 128;
;     const int bofs = BOFF + (wn * 32 * NBW + r) * 128;
; DI void phase_p1(const Params& P, unsigned char* lds) {
;     ...
;         f32x16 acc[2][4];
; #pragma unroll
;         for (int a = 0; a < 2; ++a)
; #pragma unroll
;             for (int b = 0; b < 4; ++b) acc[a][b] = zero16();
.LBB0_145:
	v_lshrrev_b32_e32 v16, 5, v14
	v_lshrrev_b32_e32 v18, 1, v13
	v_and_b32_e32 v15, 31, v13
	v_lshrrev_b32_e32 v17, 6, v13
	v_bfe_u32 v13, v13, 1, 3
	v_bitop3_b32 v19, v16, v18, 7 bitop3:0x78
	v_lshlrev_b32_e32 v143, 4, v19
	v_bitop3_b32 v19, v16, v13, 2 bitop3:0x36
	v_lshlrev_b32_e32 v144, 4, v19
	v_bitop3_b32 v19, v16, v13, 4 bitop3:0x36
	v_bitop3_b32 v13, v16, v13, 6 bitop3:0x36
	s_mov_b32 s1, 0x1ffffc0
	v_lshlrev_b32_e32 v146, 4, v13
	v_and_or_b32 v13, v18, s1, v15
	v_lshlrev_b32_e32 v12, 7, v12
	s_movk_i32 s1, 0x80
	v_and_or_b32 v12, v12, s1, v15
	v_lshrrev_b32_e32 v14, 3, v14
	v_lshlrev_b32_e32 v148, 7, v12
	v_add3_u32 v12, v11, s20, v6
	v_lshlrev_b16_e32 v6, 3, v17
	v_or_b32_e32 v11, v6, v14
	v_sub_u16_e32 v2, v11, v2
	v_and_b32_e32 v2, 31, v2
	v_lshl_add_u32 v6, v2, 2, v7
	v_sub_u16_e32 v2, v11, v3
	v_and_b32_e32 v2, 31, v2
	v_lshl_add_u32 v2, v2, 2, v8
	v_ashrrev_i32_e32 v3, 31, v2
	v_lshlrev_b64 v[2:3], 11, v[2:3]
	v_lshl_add_u64 v[2:3], v[2:3], 0, s[2:3]
	v_lshl_add_u64 v[2:3], v[2:3], 0, v[138:139]
	v_lshl_add_u64 v[134:135], s[10:11], 0, v[2:3]
	v_sub_u16_e32 v2, v11, v4
	v_and_b32_e32 v2, 31, v2
	v_lshl_add_u32 v2, v2, 2, v9
	v_ashrrev_i32_e32 v3, 31, v2
	v_lshlrev_b64 v[2:3], 11, v[2:3]
	v_lshl_add_u64 v[2:3], v[2:3], 0, s[2:3]
	v_lshl_add_u64 v[2:3], v[2:3], 0, v[138:139]
	v_lshl_add_u64 v[136:137], s[10:11], 0, v[2:3]
	v_sub_u16_e32 v2, v11, v5
	v_and_b32_e32 v2, 31, v2
	v_lshl_add_u32 v2, v2, 2, v10
	v_ashrrev_i32_e32 v3, 31, v2
	v_ashrrev_i32_e32 v7, 31, v6
	v_lshlrev_b64 v[2:3], 11, v[2:3]
	v_lshlrev_b32_e32 v147, 7, v13
	v_ashrrev_i32_e32 v13, 31, v12
	v_lshlrev_b64 v[6:7], 11, v[6:7]
	v_lshl_add_u64 v[2:3], v[2:3], 0, s[2:3]
	v_lshlrev_b64 v[12:13], 11, v[12:13]
	v_readlane_b32 s18, v223, 0
	v_lshl_add_u64 v[6:7], v[6:7], 0, s[2:3]
	v_lshl_add_u64 v[2:3], v[2:3], 0, v[138:139]
	v_or_b32_e32 v12, v12, v138
	v_readlane_b32 s19, v223, 1
	v_lshl_add_u64 v[6:7], v[6:7], 0, v[138:139]
	v_lshl_add_u64 v[140:141], s[10:11], 0, v[2:3]
	v_mov_b32_e32 v2, 0
	v_lshlrev_b32_e32 v145, 4, v19
	v_lshl_add_u64 v[130:131], s[18:19], 0, v[12:13]
	v_lshl_add_u64 v[132:133], s[10:11], 0, v[6:7]
	s_mov_b32 s1, 0
	s_mov_b64 s[2:3], 0
	s_mov_b32 s18, 0x10000
	v_mov_b32_e32 v3, v2
	v_mov_b32_e32 v4, v2
	v_mov_b32_e32 v5, v2
	v_mov_b32_e32 v6, v2
	v_mov_b32_e32 v7, v2
	v_mov_b32_e32 v8, v2
	v_mov_b32_e32 v9, v2
	v_mov_b32_e32 v10, v2
	v_mov_b32_e32 v11, v2
	v_mov_b32_e32 v12, v2
	v_mov_b32_e32 v13, v2
	v_mov_b32_e32 v14, v2
	v_mov_b32_e32 v15, v2
	v_mov_b32_e32 v16, v2
	v_mov_b32_e32 v17, v2
	v_mov_b32_e32 v34, v2
	v_mov_b32_e32 v35, v2
	v_mov_b32_e32 v36, v2
	v_mov_b32_e32 v37, v2
	v_mov_b32_e32 v38, v2
	v_mov_b32_e32 v39, v2
	v_mov_b32_e32 v40, v2
	v_mov_b32_e32 v41, v2
	v_mov_b32_e32 v42, v2
	v_mov_b32_e32 v43, v2
	v_mov_b32_e32 v44, v2
	v_mov_b32_e32 v45, v2
	v_mov_b32_e32 v46, v2
	v_mov_b32_e32 v47, v2
	v_mov_b32_e32 v48, v2
	v_mov_b32_e32 v49, v2
	v_mov_b32_e32 v18, v2
	v_mov_b32_e32 v19, v2
	v_mov_b32_e32 v20, v2
	v_mov_b32_e32 v21, v2
	v_mov_b32_e32 v22, v2
	v_mov_b32_e32 v23, v2
	v_mov_b32_e32 v24, v2
	v_mov_b32_e32 v25, v2
	v_mov_b32_e32 v26, v2
	v_mov_b32_e32 v27, v2
	v_mov_b32_e32 v28, v2
	v_mov_b32_e32 v29, v2
	v_mov_b32_e32 v30, v2
	v_mov_b32_e32 v31, v2
	v_mov_b32_e32 v32, v2
	v_mov_b32_e32 v33, v2
	v_mov_b32_e32 v50, v2
	v_mov_b32_e32 v51, v2
	v_mov_b32_e32 v52, v2
	v_mov_b32_e32 v53, v2
	v_mov_b32_e32 v54, v2
	v_mov_b32_e32 v55, v2
	v_mov_b32_e32 v56, v2
	v_mov_b32_e32 v57, v2
	v_mov_b32_e32 v58, v2
	v_mov_b32_e32 v59, v2
	v_mov_b32_e32 v60, v2
	v_mov_b32_e32 v61, v2
	v_mov_b32_e32 v62, v2
	v_mov_b32_e32 v63, v2
	v_mov_b32_e32 v64, v2
	v_mov_b32_e32 v65, v2
	v_mov_b32_e32 v66, v2
	v_mov_b32_e32 v67, v2
	v_mov_b32_e32 v68, v2
	v_mov_b32_e32 v69, v2
	v_mov_b32_e32 v70, v2
	v_mov_b32_e32 v71, v2
	v_mov_b32_e32 v72, v2
	v_mov_b32_e32 v73, v2
	v_mov_b32_e32 v74, v2
	v_mov_b32_e32 v75, v2
	v_mov_b32_e32 v76, v2
	v_mov_b32_e32 v77, v2
	v_mov_b32_e32 v78, v2
	v_mov_b32_e32 v79, v2
	v_mov_b32_e32 v80, v2
	v_mov_b32_e32 v81, v2
	v_mov_b32_e32 v98, v2
	v_mov_b32_e32 v99, v2
	v_mov_b32_e32 v100, v2
	v_mov_b32_e32 v101, v2
	v_mov_b32_e32 v102, v2
	v_mov_b32_e32 v103, v2
	v_mov_b32_e32 v104, v2
	v_mov_b32_e32 v105, v2
	v_mov_b32_e32 v106, v2
	v_mov_b32_e32 v107, v2
	v_mov_b32_e32 v108, v2
	v_mov_b32_e32 v109, v2
	v_mov_b32_e32 v110, v2
	v_mov_b32_e32 v111, v2
	v_mov_b32_e32 v112, v2
	v_mov_b32_e32 v113, v2
	v_mov_b32_e32 v82, v2
	v_mov_b32_e32 v83, v2
	v_mov_b32_e32 v84, v2
	v_mov_b32_e32 v85, v2
	v_mov_b32_e32 v86, v2
	v_mov_b32_e32 v87, v2
	v_mov_b32_e32 v88, v2
	v_mov_b32_e32 v89, v2
	v_mov_b32_e32 v90, v2
	v_mov_b32_e32 v91, v2
	v_mov_b32_e32 v92, v2
	v_mov_b32_e32 v93, v2
	v_mov_b32_e32 v94, v2
	v_mov_b32_e32 v95, v2
	v_mov_b32_e32 v96, v2
	v_mov_b32_e32 v97, v2
	v_mov_b32_e32 v114, v2
	v_mov_b32_e32 v115, v2
	v_mov_b32_e32 v116, v2
	v_mov_b32_e32 v117, v2
	v_mov_b32_e32 v118, v2
	v_mov_b32_e32 v119, v2
	v_mov_b32_e32 v120, v2
	v_mov_b32_e32 v121, v2
	v_mov_b32_e32 v122, v2
	v_mov_b32_e32 v123, v2
	v_mov_b32_e32 v124, v2
	v_mov_b32_e32 v125, v2
	v_mov_b32_e32 v126, v2
	v_mov_b32_e32 v127, v2
	v_mov_b32_e32 v128, v2
	v_mov_b32_e32 v129, v2
	s_waitcnt vmcnt(0) lgkmcnt(0)
	s_barrier
	v_mov_b32_e32 v138, v147
	v_mov_b32_e32 v149, v148
	s_add_u32 s2, s2, 0x80
	s_addc_u32 s3, s3, 0
	s_add_i32 s18, s18, 0x10000
	v_add_u32_e32 v252, v138, v143
	v_add_u32_e32 v253, v149, v143
	ds_read_b128 v[224:227], v252
	ds_read_b128 v[232:235], v253 offset:32768
	ds_read_b128 v[228:231], v252 offset:4096
	ds_read_b128 v[236:239], v253 offset:36864
	ds_read_b128 v[240:243], v253 offset:40960
	ds_read_b128 v[244:247], v253 offset:45056
; #define MFMA(a, b, c) __builtin_amdgcn_mfma_f32_32x32x16_bf16((a), (b), (c), 0, 0, 0)
; #define GEMM_ISSUE(KT, ST) do { const int k1_ = (KT) << 6; unsigned char* d_ = ldst + (ST) * STAGE; \
;         _Pragma("unroll") for (int j_ = 0; j_ < 4; ++j_) dma16(ap + (size_t)(64 * j_) * lda + k1_, d_ + j_ * 8192); \
;         _Pragma("unroll") for (int j_ = 0; j_ < NBW; ++j_) dma16(bp + bro[j_] + k1_, d_ + BOFF + j_ * 8192); } while (0)
; template <int NBW>
; DI void gemm_mainloop(f32x16 (&acc)[2][NBW], const bf16_t* A, size_t lda, int m0, const bf16_t* Bt, size_t ldb, int n0, int K, unsigned char* lds, bool pre = false, bool only_issue = false) {
;     ...
;     for (int kt = 0; kt < nk; ++kt) {
;         const unsigned char* st = lds + (kt & 1) * STAGE;
; #pragma unroll
;         for (int s = 0; s < 4; ++s) {
;             if (s == 1 && kt + 1 < nk) GEMM_ISSUE(kt + 1, (kt + 1) & 1);
;             bf16x8 a[2], b[NBW];
; #pragma unroll
;             for (int mb = 0; mb < 2; ++mb) a[mb] = *(const bf16x8*)(st + aofs + mb * 4096 + xo[s]);
; #pragma unroll
;             for (int nb = 0; nb < NBW; ++nb) b[nb] = *(const bf16x8*)(st + bofs + nb * 4096 + xo[s]);
; #pragma unroll
;             for (int mb = 0; mb < 2; ++mb)
; #pragma unroll
;                 for (int nb = 0; nb < NBW; ++nb) acc[mb][nb] = MFMA(a[mb], b[nb], acc[mb][nb]);
;         }
;         __syncthreads();
.Lp1_kloop:
	s_waitcnt lgkmcnt(4)
	v_mfma_f32_32x32x16_bf16 v[114:129], v[224:227], v[232:235], v[114:129]
	v_add_u32_e32 v252, v138, v144
	v_add_u32_e32 v253, v149, v144
	ds_read_b128 v[150:153], v252
	s_waitcnt lgkmcnt(4)
	v_mfma_f32_32x32x16_bf16 v[50:65], v[228:231], v[232:235], v[50:65]
	ds_read_b128 v[170:173], v253 offset:32768
	s_waitcnt lgkmcnt(4)
	v_mfma_f32_32x32x16_bf16 v[82:97], v[224:227], v[236:239], v[82:97]
	ds_read_b128 v[166:169], v252 offset:4096
	v_mfma_f32_32x32x16_bf16 v[18:33], v[228:231], v[236:239], v[18:33]
	ds_read_b128 v[174:177], v253 offset:36864
	s_waitcnt lgkmcnt(5)
	v_mfma_f32_32x32x16_bf16 v[98:113], v[224:227], v[240:243], v[98:113]
	ds_read_b128 v[178:181], v253 offset:40960
	v_mfma_f32_32x32x16_bf16 v[34:49], v[228:231], v[240:243], v[34:49]
	ds_read_b128 v[182:185], v253 offset:45056
	s_waitcnt lgkmcnt(6)
	v_mfma_f32_32x32x16_bf16 v[66:81], v[224:227], v[244:247], v[66:81]
	v_mfma_f32_32x32x16_bf16 v[2:17], v[228:231], v[244:247], v[2:17]
	s_waitcnt lgkmcnt(4)
	v_mfma_f32_32x32x16_bf16 v[114:129], v[150:153], v[170:173], v[114:129]
	v_add_u32_e32 v252, v138, v145
	v_add_u32_e32 v253, v149, v145
	ds_read_b128 v[224:227], v252
	s_waitcnt lgkmcnt(4)
	v_mfma_f32_32x32x16_bf16 v[50:65], v[166:169], v[170:173], v[50:65]
	ds_read_b128 v[232:235], v253 offset:32768
	s_waitcnt lgkmcnt(4)
	v_mfma_f32_32x32x16_bf16 v[82:97], v[150:153], v[174:177], v[82:97]
	ds_read_b128 v[228:231], v252 offset:4096
	v_mfma_f32_32x32x16_bf16 v[18:33], v[166:169], v[174:177], v[18:33]
	ds_read_b128 v[236:239], v253 offset:36864
	s_waitcnt lgkmcnt(5)
	v_mfma_f32_32x32x16_bf16 v[98:113], v[150:153], v[178:181], v[98:113]
	ds_read_b128 v[240:243], v253 offset:40960
	v_mfma_f32_32x32x16_bf16 v[34:49], v[166:169], v[178:181], v[34:49]
	ds_read_b128 v[244:247], v253 offset:45056
	s_waitcnt lgkmcnt(6)
	v_mfma_f32_32x32x16_bf16 v[66:81], v[150:153], v[182:185], v[66:81]
	v_mfma_f32_32x32x16_bf16 v[2:17], v[166:169], v[182:185], v[2:17]
	s_waitcnt lgkmcnt(4)
	v_mfma_f32_32x32x16_bf16 v[114:129], v[224:227], v[232:235], v[114:129]
	v_add_u32_e32 v252, v138, v146
	v_add_u32_e32 v253, v149, v146
	ds_read_b128 v[150:153], v252
	s_waitcnt lgkmcnt(4)
	v_mfma_f32_32x32x16_bf16 v[50:65], v[228:231], v[232:235], v[50:65]
	ds_read_b128 v[170:173], v253 offset:32768
	s_waitcnt lgkmcnt(4)
	v_mfma_f32_32x32x16_bf16 v[82:97], v[224:227], v[236:239], v[82:97]
	ds_read_b128 v[166:169], v252 offset:4096
	v_mfma_f32_32x32x16_bf16 v[18:33], v[228:231], v[236:239], v[18:33]
	ds_read_b128 v[174:177], v253 offset:36864
	s_waitcnt lgkmcnt(5)
	v_mfma_f32_32x32x16_bf16 v[98:113], v[224:227], v[240:243], v[98:113]
	ds_read_b128 v[178:181], v253 offset:40960
	v_mfma_f32_32x32x16_bf16 v[34:49], v[228:231], v[240:243], v[34:49]
	ds_read_b128 v[182:185], v253 offset:45056
	s_waitcnt lgkmcnt(6)
	v_mfma_f32_32x32x16_bf16 v[66:81], v[224:227], v[244:247], v[66:81]
	v_mfma_f32_32x32x16_bf16 v[2:17], v[228:231], v[244:247], v[2:17]
	v_xor_b32_e32 v138, 0x10000, v138
	v_xor_b32_e32 v149, 0x10000, v149
	s_waitcnt vmcnt(0) lgkmcnt(0)
	s_barrier
	s_cmp_eq_u32 s2, 0x800
	s_cbranch_scc1 .Lp1_klast
	s_cmp_eq_u32 s2, 0x780
	s_cbranch_scc1 .Lp1_knodma
	v_mfma_f32_32x32x16_bf16 v[114:129], v[150:153], v[170:173], v[114:129]
	v_add_u32_e32 v252, v138, v143
	v_add_u32_e32 v253, v149, v143
	ds_read_b128 v[224:227], v252
	s_and_b32 s19, s18, 0x10000
	v_add_u32_e32 v250, s19, v142
	v_lshl_add_u64 v[248:249], v[130:131], 0, s[2:3]
	s_nop 0
	v_readfirstlane_b32 s19, v250
	s_mov_b64 s[22:23], 0x1080
	v_lshl_add_u64 v[250:251], v[248:249], 0, s[22:23]
	s_mov_b32 m0, s19
	s_nop 0
	global_load_lds_dwordx4 v[250:251], off
	v_mfma_f32_32x32x16_bf16 v[50:65], v[166:169], v[170:173], v[50:65]
	ds_read_b128 v[232:235], v253 offset:32768
	s_mov_b64 s[22:23], 0x21080
	v_lshl_add_u64 v[250:251], v[248:249], 0, s[22:23]
	s_add_i32 m0, s19, 0x2000
	s_nop 0
	global_load_lds_dwordx4 v[250:251], off
	v_mfma_f32_32x32x16_bf16 v[82:97], v[150:153], v[174:177], v[82:97]
	ds_read_b128 v[228:231], v252 offset:4096
	s_mov_b64 s[22:23], 0x41080
	v_lshl_add_u64 v[250:251], v[248:249], 0, s[22:23]
	s_add_i32 m0, s19, 0x4000
	s_nop 0
	global_load_lds_dwordx4 v[250:251], off
	v_mfma_f32_32x32x16_bf16 v[18:33], v[166:169], v[174:177], v[18:33]
	ds_read_b128 v[236:239], v253 offset:36864
	s_mov_b64 s[22:23], 0x61080
	v_lshl_add_u64 v[250:251], v[248:249], 0, s[22:23]
	s_add_i32 m0, s19, 0x6000
	s_nop 0
	global_load_lds_dwordx4 v[250:251], off
	v_mfma_f32_32x32x16_bf16 v[98:113], v[150:153], v[178:181], v[98:113]
	ds_read_b128 v[240:243], v253 offset:40960
	v_lshl_add_u64 v[250:251], v[132:133], 0, s[2:3]
	s_add_i32 m0, s19, 0x8000
	s_nop 0
	global_load_lds_dwordx4 v[250:251], off
	v_mfma_f32_32x32x16_bf16 v[34:49], v[166:169], v[178:181], v[34:49]
	ds_read_b128 v[244:247], v253 offset:45056
	v_lshl_add_u64 v[250:251], v[134:135], 0, s[2:3]
	s_add_i32 m0, s19, 0xa000
	s_nop 0
	global_load_lds_dwordx4 v[250:251], off
	v_mfma_f32_32x32x16_bf16 v[66:81], v[150:153], v[182:185], v[66:81]
	v_lshl_add_u64 v[250:251], v[136:137], 0, s[2:3]
	s_add_i32 m0, s19, 0xc000
	s_nop 0
	global_load_lds_dwordx4 v[250:251], off
	v_mfma_f32_32x32x16_bf16 v[2:17], v[166:169], v[182:185], v[2:17]
	v_lshl_add_u64 v[250:251], v[140:141], 0, s[2:3]
	s_add_i32 m0, s19, 0xe000
	s_nop 0
	global_load_lds_dwordx4 v[250:251], off
	s_add_u32 s2, s2, 0x80
	s_addc_u32 s3, s3, 0
	s_add_i32 s18, s18, 0x10000
	s_branch .Lp1_kloop
.Lp1_knodma:
	v_mfma_f32_32x32x16_bf16 v[114:129], v[150:153], v[170:173], v[114:129]
	v_add_u32_e32 v252, v138, v143
	v_add_u32_e32 v253, v149, v143
	ds_read_b128 v[224:227], v252
	v_mfma_f32_32x32x16_bf16 v[50:65], v[166:169], v[170:173], v[50:65]
	ds_read_b128 v[232:235], v253 offset:32768
	v_mfma_f32_32x32x16_bf16 v[82:97], v[150:153], v[174:177], v[82:97]
	ds_read_b128 v[228:231], v252 offset:4096
	v_mfma_f32_32x32x16_bf16 v[18:33], v[166:169], v[174:177], v[18:33]
	ds_read_b128 v[236:239], v253 offset:36864
	v_mfma_f32_32x32x16_bf16 v[98:113], v[150:153], v[178:181], v[98:113]
	ds_read_b128 v[240:243], v253 offset:40960
	v_mfma_f32_32x32x16_bf16 v[34:49], v[166:169], v[178:181], v[34:49]
	ds_read_b128 v[244:247], v253 offset:45056
	v_mfma_f32_32x32x16_bf16 v[66:81], v[150:153], v[182:185], v[66:81]
	v_mfma_f32_32x32x16_bf16 v[2:17], v[166:169], v[182:185], v[2:17]
	s_add_u32 s2, s2, 0x80
	s_addc_u32 s3, s3, 0
	s_add_i32 s18, s18, 0x10000
	s_branch .Lp1_kloop
.Lp1_klast:
	v_mfma_f32_32x32x16_bf16 v[114:129], v[150:153], v[170:173], v[114:129]
	v_mfma_f32_32x32x16_bf16 v[50:65], v[166:169], v[170:173], v[50:65]
	v_mfma_f32_32x32x16_bf16 v[82:97], v[150:153], v[174:177], v[82:97]
	v_mfma_f32_32x32x16_bf16 v[18:33], v[166:169], v[174:177], v[18:33]
	v_mfma_f32_32x32x16_bf16 v[98:113], v[150:153], v[178:181], v[98:113]
	v_mfma_f32_32x32x16_bf16 v[34:49], v[166:169], v[178:181], v[34:49]
	v_mfma_f32_32x32x16_bf16 v[66:81], v[150:153], v[182:185], v[66:81]
	v_mfma_f32_32x32x16_bf16 v[2:17], v[166:169], v[182:185], v[2:17]
	s_mov_b32 s1, 16
	s_mov_b32 s19, 0x10000
	s_mov_b64 s[22:23], 0x61080

; #define MFMA(a, b, c) __builtin_amdgcn_mfma_f32_32x32x16_bf16((a), (b), (c), 0, 0, 0)
; DI f32x16 zero16() { f32x16 z; for (int i = 0; i < 16; ++i) z[i] = 0.f; return z; }
; DI void attn_prompt_item(const Params& P, unsigned char* lds, int b, int head, int qb, float qkb2) {
;     ...
;         if (kt * 64 <= qw0 + 31) {
;             f32x16 st[2];
; #pragma unroll
;             for (int kb = 0; kb < 2; ++kb) {
;                 st[kb] = zero16();
; #pragma unroll
;                 for (int s = 0; s < 8; ++s) {
;                     const bf16x8 a = *(const bf16x8*)(sb + (32 * kb + r) * 272 + (16 * s + 8 * hh) * 2);
;                     st[kb] = MFMA(a, qf[s], st[kb]);
;                 }
;             }
.LBB0_1226:
	s_and_saveexec_b64 s[22:23], s[0:1]
	s_cbranch_execz .LBB0_1228
	v_mad_u64_u32 v[16:17], s[0:1], v203, s60, v[176:177]
	v_add_u32_e32 v2, 0x4000, v16
	ds_read2_b64 v[224:227], v2 offset0:128 offset1:130
	v_add_u32_e32 v17, 0x5000, v16
	ds_read2_b64 v[228:231], v17 offset0:192 offset1:194
	v_add_u32_e32 v90, 0x6800, v16
	ds_read2_b64 v[232:235], v90 offset1:2
	v_add_u32_e32 v16, 0x7800, v16
	ds_read2_b64 v[236:239], v16 offset0:64 offset1:66
	s_waitcnt lgkmcnt(4)
	s_waitcnt lgkmcnt(3)
	v_mfma_f32_32x32x16_bf16 v[66:81], v[224:227], v[82:85], v[66:81]
	ds_read2_b64 v[224:227], v2 offset0:132 offset1:134
	s_waitcnt lgkmcnt(3)
	v_mfma_f32_32x32x16_bf16 v[50:65], v[228:231], v[82:85], v[50:65]
	ds_read2_b64 v[228:231], v17 offset0:196 offset1:198
	s_waitcnt lgkmcnt(3)
	v_mfma_f32_32x32x16_bf16 v[34:49], v[232:235], v[82:85], v[34:49]
	ds_read2_b64 v[232:235], v90 offset0:4 offset1:6
	s_waitcnt lgkmcnt(3)
	v_mfma_f32_32x32x16_bf16 v[18:33], v[236:239], v[82:85], v[18:33]
	ds_read2_b64 v[236:239], v16 offset0:68 offset1:70
	s_waitcnt lgkmcnt(3)
	v_mfma_f32_32x32x16_bf16 v[66:81], v[224:227], v[12:15], v[66:81]
	ds_read2_b64 v[224:227], v2 offset0:136 offset1:138
	s_waitcnt lgkmcnt(3)
	v_mfma_f32_32x32x16_bf16 v[50:65], v[228:231], v[12:15], v[50:65]
	ds_read2_b64 v[228:231], v17 offset0:200 offset1:202
	s_waitcnt lgkmcnt(3)
	v_mfma_f32_32x32x16_bf16 v[34:49], v[232:235], v[12:15], v[34:49]
	ds_read2_b64 v[232:235], v90 offset0:8 offset1:10
	s_waitcnt lgkmcnt(3)
	v_mfma_f32_32x32x16_bf16 v[18:33], v[236:239], v[12:15], v[18:33]
	ds_read2_b64 v[236:239], v16 offset0:72 offset1:74
	s_waitcnt lgkmcnt(3)
	v_mfma_f32_32x32x16_bf16 v[66:81], v[224:227], v[8:11], v[66:81]
	ds_read2_b64 v[224:227], v2 offset0:140 offset1:142
	s_waitcnt lgkmcnt(3)
	v_mfma_f32_32x32x16_bf16 v[50:65], v[228:231], v[8:11], v[50:65]
	ds_read2_b64 v[228:231], v17 offset0:204 offset1:206
	s_waitcnt lgkmcnt(3)
	v_mfma_f32_32x32x16_bf16 v[34:49], v[232:235], v[8:11], v[34:49]
	ds_read2_b64 v[232:235], v90 offset0:12 offset1:14
	s_waitcnt lgkmcnt(3)
	v_mfma_f32_32x32x16_bf16 v[18:33], v[236:239], v[8:11], v[18:33]
	ds_read2_b64 v[236:239], v16 offset0:76 offset1:78
	s_waitcnt lgkmcnt(3)
	v_mfma_f32_32x32x16_bf16 v[66:81], v[224:227], v[4:7], v[66:81]
	s_waitcnt lgkmcnt(2)
	v_mfma_f32_32x32x16_bf16 v[50:65], v[228:231], v[4:7], v[50:65]
	s_waitcnt lgkmcnt(1)
	v_mfma_f32_32x32x16_bf16 v[34:49], v[232:235], v[4:7], v[34:49]
	s_waitcnt lgkmcnt(0)
	v_mfma_f32_32x32x16_bf16 v[18:33], v[236:239], v[4:7], v[18:33]
.LBB0_1228:
	s_or_b64 exec, exec, s[22:23]
	s_add_i32 s0, s66, 64
	v_cmp_le_i32_e32 vcc, s0, v205
	v_mov_b32_e32 v2, 0xf149f2ca
	s_mov_b64 s[0:1], 0
	s_and_saveexec_b64 s[22:23], vcc
	s_cbranch_execz .LBB0_1233
	v_add_u32_e32 v2, s29, v208
	ds_read_b128 v[224:227], v2
	ds_read_b128 v[228:231], v2 offset:32
	ds_read_b128 v[232:235], v2 offset:64
	ds_read_b128 v[236:239], v2 offset:96
	v_add_u32_e32 v12, s29, v210
	s_add_i32 s0, s66, 0x7f
	v_cmp_gt_u32_e32 vcc, s0, v165
	s_waitcnt lgkmcnt(4)
	s_waitcnt lgkmcnt(3)
	v_mfma_f32_32x32x16_bf16 v[98:113], v[224:227], v[114:117], 0
	ds_read_b128 v[224:227], v2 offset:128
	s_waitcnt lgkmcnt(3)
	v_mfma_f32_32x32x16_bf16 v[98:113], v[228:231], v[118:121], v[98:113]
	ds_read_b128 v[228:231], v2 offset:160
	v_add_u32_e32 v9, s66, v169
	v_add_u32_e32 v8, 64, v9
	v_cmp_gt_i32_e64 s[0:1], v8, v168
	s_and_b64 s[0:1], vcc, s[0:1]
	v_add_u32_e32 v11, 0x49, v9
	s_waitcnt lgkmcnt(3)
	v_mfma_f32_32x32x16_bf16 v[98:113], v[232:235], v[122:125], v[98:113]
	ds_read_b128 v[232:235], v2 offset:192
	s_waitcnt lgkmcnt(3)
	v_mfma_f32_32x32x16_bf16 v[98:113], v[236:239], v[126:129], v[98:113]
	ds_read_b128 v[236:239], v2 offset:224
	s_waitcnt lgkmcnt(3)
	v_mfma_f32_32x32x16_bf16 v[98:113], v[224:227], v[130:133], v[98:113]
	ds_read_b128 v[224:227], v2 offset:8704
	s_waitcnt lgkmcnt(3)
	v_mfma_f32_32x32x16_bf16 v[98:113], v[228:231], v[134:137], v[98:113]
	ds_read_b128 v[228:231], v2 offset:8736
	s_waitcnt lgkmcnt(3)
	v_mfma_f32_32x32x16_bf16 v[98:113], v[232:235], v[138:141], v[98:113]
	ds_read_b128 v[232:235], v2 offset:8768
	s_waitcnt lgkmcnt(3)
	v_mfma_f32_32x32x16_bf16 v[98:113], v[236:239], v[142:145], v[98:113]
	ds_read_b128 v[236:239], v2 offset:8800
	s_waitcnt lgkmcnt(3)
	v_mfma_f32_32x32x16_bf16 v[82:97], v[224:227], v[114:117], 0
	ds_read_b128 v[224:227], v2 offset:8832
	s_waitcnt lgkmcnt(3)
	v_mfma_f32_32x32x16_bf16 v[82:97], v[228:231], v[118:121], v[82:97]
	ds_read_b128 v[228:231], v2 offset:8864
	s_waitcnt lgkmcnt(3)
	v_mfma_f32_32x32x16_bf16 v[82:97], v[232:235], v[122:125], v[82:97]
	ds_read_b128 v[232:235], v2 offset:8896
	s_waitcnt lgkmcnt(3)
	v_mfma_f32_32x32x16_bf16 v[82:97], v[236:239], v[126:129], v[82:97]
	ds_read_b128 v[236:239], v2 offset:8928
	s_waitcnt lgkmcnt(3)
	v_mfma_f32_32x32x16_bf16 v[82:97], v[224:227], v[130:133], v[82:97]
	s_waitcnt lgkmcnt(2)
	v_mfma_f32_32x32x16_bf16 v[82:97], v[228:231], v[134:137], v[82:97]
	s_waitcnt lgkmcnt(1)
	v_mfma_f32_32x32x16_bf16 v[82:97], v[232:235], v[138:141], v[82:97]
	s_waitcnt lgkmcnt(0)
	v_mfma_f32_32x32x16_bf16 v[82:97], v[236:239], v[142:145], v[82:97]
	s_cbranch_vccz .Lattn_nomask_0
; DI void attn_prompt_item(const Params& P, unsigned char* lds, int b, int head, int qb, float qkb2) {
;     ...
;             const bool need_mask = (kt * 64 + 63 > qw0);
;             float mx = -1e30f;
; #pragma unroll
;             for (int kb = 0; kb < 2; ++kb)
; #pragma unroll
;                 for (int g = 0; g < 4; ++g) {
;                     const f32x4 bz = *(const f32x4*)(sb + BOFF + (32 * kb + 8 * g + 4 * hh) * 4);
; #pragma unroll
;                     for (int e = 0; e < 4; ++e) {
;                         float v = st[kb][4 * g + e] * ATT_SC + bz[e];
;                         if (need_mask) { const int key = kt * 64 + 32 * kb + 8 * g + 4 * hh + e; v = (key > myq) ? -1e30f : v; }
;                         st[kb][4 * g + e] = v; mx = fmaxf(mx, v);
;                     }
;                 }
	ds_read_b128 v[4:7], v12
	ds_read_b128 v[14:17], v12 offset:32
	s_waitcnt lgkmcnt(1)
	v_fmamk_f32 v2, v98, 0x3e0293ee, v4
	v_cndmask_b32_e64 v2, v2, v177, s[0:1]
	v_cmp_ge_i32_e64 s[0:1], v8, v168
	v_fmamk_f32 v4, v99, 0x3e0293ee, v5
	s_and_b64 s[0:1], vcc, s[0:1]
	v_fmamk_f32 v5, v100, 0x3e0293ee, v6
	v_add_u32_e32 v6, 0x42, v9
	v_cndmask_b32_e64 v4, v4, v177, s[0:1]
	v_cmp_gt_i32_e64 s[0:1], v6, v168
	s_and_b64 s[0:1], vcc, s[0:1]
	v_add_u32_e32 v6, 0x43, v9
	v_cndmask_b32_e64 v5, v5, v177, s[0:1]
	v_cmp_gt_i32_e64 s[0:1], v6, v168
	v_fmac_f32_e32 v7, 0x3e0293ee, v101
	s_and_b64 s[0:1], vcc, s[0:1]
	v_cndmask_b32_e64 v6, v7, v177, s[0:1]
	v_add_u32_e32 v7, 0x48, v9
	v_max3_f32 v8, v2, s61, v4
	v_cmp_gt_i32_e64 s[0:1], v7, v168
	v_max3_f32 v10, v8, v5, v6
	s_waitcnt lgkmcnt(0)
	v_fmamk_f32 v8, v102, 0x3e0293ee, v14
	s_and_b64 s[0:1], vcc, s[0:1]
	v_cndmask_b32_e64 v7, v8, v177, s[0:1]
	v_cmp_gt_i32_e64 s[0:1], v11, v168
	v_fmamk_f32 v8, v103, 0x3e0293ee, v15
	s_and_b64 s[0:1], vcc, s[0:1]
	v_add_u32_e32 v11, 0x4a, v9
	v_cndmask_b32_e64 v8, v8, v177, s[0:1]
	v_cmp_gt_i32_e64 s[0:1], v11, v168
	v_max3_f32 v13, v10, v7, v8
	v_fmamk_f32 v10, v104, 0x3e0293ee, v16
	s_and_b64 s[0:1], vcc, s[0:1]
	v_add_u32_e32 v11, 0x4b, v9
	v_cndmask_b32_e64 v10, v10, v177, s[0:1]
	v_cmp_gt_i32_e64 s[0:1], v11, v168
	v_fmac_f32_e32 v17, 0x3e0293ee, v105
	s_and_b64 s[0:1], vcc, s[0:1]
	v_cndmask_b32_e64 v11, v17, v177, s[0:1]
	ds_read_b128 v[14:17], v12 offset:64
	v_max3_f32 v98, v13, v10, v11
	v_add_u32_e32 v13, 0x50, v9
	v_cmp_gt_i32_e64 s[0:1], v13, v168
	s_and_b64 s[0:1], vcc, s[0:1]
	s_waitcnt lgkmcnt(0)
	v_fmamk_f32 v14, v106, 0x3e0293ee, v14
	v_cndmask_b32_e64 v13, v14, v177, s[0:1]
	v_fmamk_f32 v14, v107, 0x3e0293ee, v15
	v_add_u32_e32 v15, 0x51, v9
	v_cmp_gt_i32_e64 s[0:1], v15, v168
	s_and_b64 s[0:1], vcc, s[0:1]
	v_fmamk_f32 v15, v108, 0x3e0293ee, v16
	v_add_u32_e32 v16, 0x52, v9
	v_cndmask_b32_e64 v14, v14, v177, s[0:1]
	v_cmp_gt_i32_e64 s[0:1], v16, v168
	s_and_b64 s[0:1], vcc, s[0:1]
	v_add_u32_e32 v16, 0x53, v9
	v_cndmask_b32_e64 v15, v15, v177, s[0:1]
	v_cmp_gt_i32_e64 s[0:1], v16, v168
	v_fmac_f32_e32 v17, 0x3e0293ee, v109
	s_and_b64 s[0:1], vcc, s[0:1]
	v_max3_f32 v98, v98, v13, v14
	v_cndmask_b32_e64 v16, v17, v177, s[0:1]
	v_max3_f32 v102, v98, v15, v16
	ds_read_b128 v[98:101], v12 offset:96
	v_add_u32_e32 v17, 0x58, v9
	v_cmp_gt_i32_e64 s[0:1], v17, v168
	s_and_b64 s[0:1], vcc, s[0:1]
	v_add_u32_e32 v106, 0x60, v9
	s_waitcnt lgkmcnt(0)
	v_fmamk_f32 v98, v110, 0x3e0293ee, v98
	v_cndmask_b32_e64 v17, v98, v177, s[0:1]
	v_fmamk_f32 v98, v111, 0x3e0293ee, v99
	v_add_u32_e32 v99, 0x59, v9
	v_cmp_gt_i32_e64 s[0:1], v99, v168
	s_and_b64 s[0:1], vcc, s[0:1]
	v_fmamk_f32 v99, v112, 0x3e0293ee, v100
	v_add_u32_e32 v100, 0x5a, v9
	v_cndmask_b32_e64 v98, v98, v177, s[0:1]
	v_cmp_gt_i32_e64 s[0:1], v100, v168
	s_and_b64 s[0:1], vcc, s[0:1]
	v_add_u32_e32 v100, 0x5b, v9
	v_cndmask_b32_e64 v99, v99, v177, s[0:1]
	v_cmp_gt_i32_e64 s[0:1], v100, v168
	v_fmac_f32_e32 v101, 0x3e0293ee, v113
	s_and_b64 s[0:1], vcc, s[0:1]
	v_max3_f32 v102, v102, v17, v98
	v_cndmask_b32_e64 v100, v101, v177, s[0:1]
	v_max3_f32 v101, v102, v99, v100
	ds_read_b128 v[102:105], v12 offset:128
	v_cmp_gt_i32_e64 s[0:1], v106, v168
	s_and_b64 s[0:1], vcc, s[0:1]
	v_add_u32_e32 v106, 0x68, v9
	s_waitcnt lgkmcnt(0)
	v_fmamk_f32 v82, v82, 0x3e0293ee, v102
	v_add_u32_e32 v102, 0x61, v9
	v_cndmask_b32_e64 v82, v82, v177, s[0:1]
	v_cmp_gt_i32_e64 s[0:1], v102, v168
	v_fmamk_f32 v83, v83, 0x3e0293ee, v103
	s_and_b64 s[0:1], vcc, s[0:1]
	v_add_u32_e32 v102, 0x62, v9
	v_cndmask_b32_e64 v83, v83, v177, s[0:1]
	v_cmp_gt_i32_e64 s[0:1], v102, v168
	v_fmamk_f32 v84, v84, 0x3e0293ee, v104
	s_and_b64 s[0:1], vcc, s[0:1]
	v_fmac_f32_e32 v105, 0x3e0293ee, v85
	v_add_u32_e32 v85, 0x63, v9
	v_cndmask_b32_e64 v84, v84, v177, s[0:1]
	v_cmp_gt_i32_e64 s[0:1], v85, v168
	s_and_b64 s[0:1], vcc, s[0:1]
	v_max3_f32 v101, v101, v82, v83
	v_cndmask_b32_e64 v85, v105, v177, s[0:1]
	ds_read_b128 v[102:105], v12 offset:160
	v_cmp_gt_i32_e64 s[0:1], v106, v168
	s_and_b64 s[0:1], vcc, s[0:1]
	v_add_u32_e32 v106, 0x70, v9
	v_max3_f32 v101, v101, v84, v85
	s_waitcnt lgkmcnt(0)
	v_fmamk_f32 v86, v86, 0x3e0293ee, v102
	v_add_u32_e32 v102, 0x69, v9
	v_cndmask_b32_e64 v86, v86, v177, s[0:1]
	v_cmp_gt_i32_e64 s[0:1], v102, v168
	v_fmamk_f32 v87, v87, 0x3e0293ee, v103
	s_and_b64 s[0:1], vcc, s[0:1]
	v_add_u32_e32 v102, 0x6a, v9
	v_cndmask_b32_e64 v87, v87, v177, s[0:1]
	v_cmp_gt_i32_e64 s[0:1], v102, v168
	v_fmamk_f32 v88, v88, 0x3e0293ee, v104
	s_and_b64 s[0:1], vcc, s[0:1]
	v_fmac_f32_e32 v105, 0x3e0293ee, v89
	v_add_u32_e32 v89, 0x6b, v9
	v_cndmask_b32_e64 v88, v88, v177, s[0:1]
	v_cmp_gt_i32_e64 s[0:1], v89, v168
	s_and_b64 s[0:1], vcc, s[0:1]
	v_max3_f32 v101, v101, v86, v87
	v_cndmask_b32_e64 v89, v105, v177, s[0:1]
	ds_read_b128 v[102:105], v12 offset:192
	v_cmp_gt_i32_e64 s[0:1], v106, v168
	s_and_b64 s[0:1], vcc, s[0:1]
	v_max3_f32 v101, v101, v88, v89
	s_waitcnt lgkmcnt(0)
	v_fmamk_f32 v90, v90, 0x3e0293ee, v102
	v_add_u32_e32 v102, 0x71, v9
	v_cndmask_b32_e64 v90, v90, v177, s[0:1]
	v_cmp_gt_i32_e64 s[0:1], v102, v168
	v_fmamk_f32 v91, v91, 0x3e0293ee, v103
	s_and_b64 s[0:1], vcc, s[0:1]
	v_add_u32_e32 v102, 0x72, v9
	v_cndmask_b32_e64 v91, v91, v177, s[0:1]
	v_cmp_gt_i32_e64 s[0:1], v102, v168
	v_fmamk_f32 v92, v92, 0x3e0293ee, v104
	s_and_b64 s[0:1], vcc, s[0:1]
	v_fmac_f32_e32 v105, 0x3e0293ee, v93
	v_add_u32_e32 v93, 0x73, v9
	v_cndmask_b32_e64 v92, v92, v177, s[0:1]
	v_cmp_gt_i32_e64 s[0:1], v93, v168
	s_and_b64 s[0:1], vcc, s[0:1]
	v_max3_f32 v101, v101, v90, v91
	v_cndmask_b32_e64 v93, v105, v177, s[0:1]
	ds_read_b128 v[102:105], v12 offset:224
	v_add_u32_e32 v12, 0x78, v9
	v_cmp_gt_i32_e64 s[0:1], v12, v168
	s_and_b64 s[0:1], vcc, s[0:1]
	v_max3_f32 v106, v101, v92, v93
	s_waitcnt lgkmcnt(0)
	v_fmamk_f32 v94, v94, 0x3e0293ee, v102
	v_cndmask_b32_e64 v12, v94, v177, s[0:1]
	v_fmamk_f32 v94, v95, 0x3e0293ee, v103
	v_add_u32_e32 v95, 0x79, v9
	v_cmp_gt_i32_e64 s[0:1], v95, v168
	s_and_b64 s[0:1], vcc, s[0:1]
	v_fmamk_f32 v95, v96, 0x3e0293ee, v104
	v_add_u32_e32 v96, 0x7a, v9
	v_cndmask_b32_e64 v101, v94, v177, s[0:1]
	v_cmp_gt_i32_e64 s[0:1], v96, v168
	s_and_b64 s[0:1], vcc, s[0:1]
	v_add_u32_e32 v9, 0x7b, v9
	v_cndmask_b32_e64 v214, v95, v177, s[0:1]
	v_cmp_gt_i32_e64 s[0:1], v9, v168
	v_fmac_f32_e32 v105, 0x3e0293ee, v97
	s_and_b64 vcc, vcc, s[0:1]
	v_max3_f32 v94, v106, v12, v101
	v_cndmask_b32_e32 v9, v105, v177, vcc
	v_max3_f32 v94, v94, v214, v9
	s_branch .Lattn_join_0

; DI float ex2(float x) { return __builtin_amdgcn_exp2f(x); }
; DI void attn_prompt_item(const Params& P, unsigned char* lds, int b, int head, int qb, float qkb2) {
;     ...
;             float ps = 0.f;
; #pragma unroll
;             for (int kb = 0; kb < 2; ++kb)
; #pragma unroll
;                 for (int i = 0; i < 16; ++i) { const float pv = ex2(st[kb][i] - m_new); st[kb][i] = pv; ps += pv; }
;             if (grew) {
;                 const float alpha = ex2(m_run - m_new); m_run = m_new;
;                 l_run = l_run * alpha;
; #pragma unroll
;                 for (int db = 0; db < 4; ++db) o[db] = o[db] * alpha;
;             }
;             l_run += ps;
; #pragma unroll
;             for (int kb = 0; kb < 2; ++kb)
; #pragma unroll
;                 for (int sp = 0; sp < 2; ++sp) pp[kb][sp] = pack8(st[kb], sp);
;             if (late) { pending = true; pbuf = bi; }
;             else ATT_PV(sb, pp);
.LBB0_1231:
	v_sub_f32_e32 v2, v2, v215
	v_exp_f32_e32 v102, v2
	v_sub_f32_e32 v2, v4, v215
	v_exp_f32_e32 v103, v2
	v_sub_f32_e32 v2, v5, v215
	v_exp_f32_e32 v104, v2
	v_sub_f32_e32 v2, v6, v215
	v_exp_f32_e32 v105, v2
	v_sub_f32_e32 v2, v7, v215
	v_exp_f32_e32 v106, v2
	v_sub_f32_e32 v2, v8, v215
	v_exp_f32_e32 v107, v2
	v_sub_f32_e32 v2, v10, v215
	v_exp_f32_e32 v108, v2
	v_sub_f32_e32 v2, v11, v215
	v_exp_f32_e32 v109, v2
	v_sub_f32_e32 v2, v13, v215
	v_exp_f32_e32 v110, v2
	v_sub_f32_e32 v2, v14, v215
	v_exp_f32_e32 v111, v2
	v_sub_f32_e32 v2, v15, v215
	v_exp_f32_e32 v112, v2
	v_sub_f32_e32 v2, v16, v215
	v_sub_f32_e32 v4, v99, v215
	v_exp_f32_e32 v113, v2
	v_sub_f32_e32 v2, v17, v215
	v_exp_f32_e32 v17, v4
	v_sub_f32_e32 v4, v100, v215
	v_exp_f32_e32 v95, v4
	v_sub_f32_e32 v4, v82, v215
	v_exp_f32_e32 v97, v4
	v_sub_f32_e32 v4, v83, v215
	v_exp_f32_e32 v16, v4
	v_sub_f32_e32 v4, v84, v215
	v_exp_f32_e32 v94, v4
	v_sub_f32_e32 v4, v85, v215
	v_exp_f32_e32 v96, v4
	v_sub_f32_e32 v4, v86, v215
	v_exp_f32_e32 v213, v2
	v_sub_f32_e32 v2, v98, v215
	v_exp_f32_e32 v98, v4
	v_sub_f32_e32 v4, v87, v215
	v_exp_f32_e32 v86, v4
	v_sub_f32_e32 v4, v88, v215
	v_exp_f32_e32 v87, v4
	v_sub_f32_e32 v4, v89, v215
	v_exp_f32_e32 v89, v4
	v_sub_f32_e32 v4, v90, v215
	v_exp_f32_e32 v99, v4
	v_sub_f32_e32 v4, v91, v215
	v_exp_f32_e32 v88, v4
	v_sub_f32_e32 v4, v92, v215
	v_exp_f32_e32 v90, v4
	v_sub_f32_e32 v4, v93, v215
	v_exp_f32_e32 v92, v4
	v_sub_f32_e32 v4, v12, v215
	v_exp_f32_e32 v100, v4
	v_sub_f32_e32 v4, v101, v215
	v_exp_f32_e32 v91, v4
	v_sub_f32_e32 v4, v214, v215
	v_exp_f32_e32 v93, v4
	v_sub_f32_e32 v4, v9, v215
	v_exp_f32_e32 v2, v2
	v_exp_f32_e32 v101, v4
	s_mul_i32 s30, s30, 3
	s_sub_i32 s0, s24, s30
	v_cvt_pk_bf16_f32 v82, v102, v103
	v_cvt_pk_bf16_f32 v83, v104, v105
	v_cvt_pk_bf16_f32 v84, v106, v107
	v_cvt_pk_bf16_f32 v85, v108, v109
	v_cvt_pk_bf16_f32 v12, v110, v111
	v_cvt_pk_bf16_f32 v13, v112, v113
	v_cvt_pk_bf16_f32 v14, v213, v2
	v_cvt_pk_bf16_f32 v15, v17, v95
	v_cvt_pk_bf16_f32 v8, v97, v16
	v_cvt_pk_bf16_f32 v9, v94, v96
	v_cvt_pk_bf16_f32 v10, v98, v86
	v_cvt_pk_bf16_f32 v11, v87, v89
	v_cvt_pk_bf16_f32 v4, v99, v88
	v_cvt_pk_bf16_f32 v5, v90, v92
	v_cvt_pk_bf16_f32 v6, v100, v91
	v_cvt_pk_bf16_f32 v7, v93, v101
	s_andn2_b64 vcc, exec, s[10:11]
	s_cbranch_vccnz .LBB0_1235
	v_add_u32_e32 v218, s29, v211
	v_add_u32_e32 v219, 0x4000, v218
	ds_read2_b64 v[224:227], v219 offset0:128 offset1:130
	v_add_u32_e32 v220, 0x5000, v218
	ds_read2_b64 v[228:231], v220 offset0:192 offset1:194
	v_add_u32_e32 v221, 0x6800, v218
	ds_read2_b64 v[232:235], v221 offset1:2
	v_add_u32_e32 v218, 0x7800, v218
	ds_read2_b64 v[236:239], v218 offset0:64 offset1:66
	s_waitcnt lgkmcnt(4)
	s_waitcnt lgkmcnt(3)
	v_mfma_f32_32x32x16_bf16 v[66:81], v[224:227], v[82:85], v[66:81]
	ds_read2_b64 v[224:227], v219 offset0:132 offset1:134
	s_waitcnt lgkmcnt(3)
	v_mfma_f32_32x32x16_bf16 v[50:65], v[228:231], v[82:85], v[50:65]
	ds_read2_b64 v[228:231], v220 offset0:196 offset1:198
	s_waitcnt lgkmcnt(3)
	v_mfma_f32_32x32x16_bf16 v[34:49], v[232:235], v[82:85], v[34:49]
	ds_read2_b64 v[232:235], v221 offset0:4 offset1:6
	s_waitcnt lgkmcnt(3)
	v_mfma_f32_32x32x16_bf16 v[18:33], v[236:239], v[82:85], v[18:33]
	ds_read2_b64 v[236:239], v218 offset0:68 offset1:70
	s_waitcnt lgkmcnt(3)
	v_mfma_f32_32x32x16_bf16 v[66:81], v[224:227], v[12:15], v[66:81]
	ds_read2_b64 v[224:227], v219 offset0:136 offset1:138
	s_waitcnt lgkmcnt(3)
	v_mfma_f32_32x32x16_bf16 v[50:65], v[228:231], v[12:15], v[50:65]
	ds_read2_b64 v[228:231], v220 offset0:200 offset1:202
	s_waitcnt lgkmcnt(3)
	v_mfma_f32_32x32x16_bf16 v[34:49], v[232:235], v[12:15], v[34:49]
	ds_read2_b64 v[232:235], v221 offset0:8 offset1:10
	s_waitcnt lgkmcnt(3)
	v_mfma_f32_32x32x16_bf16 v[18:33], v[236:239], v[12:15], v[18:33]
	ds_read2_b64 v[236:239], v218 offset0:72 offset1:74
	s_waitcnt lgkmcnt(3)
	v_mfma_f32_32x32x16_bf16 v[66:81], v[224:227], v[8:11], v[66:81]
	ds_read2_b64 v[224:227], v219 offset0:140 offset1:142
	s_waitcnt lgkmcnt(3)
	v_mfma_f32_32x32x16_bf16 v[50:65], v[228:231], v[8:11], v[50:65]
	ds_read2_b64 v[228:231], v220 offset0:204 offset1:206
	s_waitcnt lgkmcnt(3)
	v_mfma_f32_32x32x16_bf16 v[34:49], v[232:235], v[8:11], v[34:49]
	ds_read2_b64 v[232:235], v221 offset0:12 offset1:14
	s_waitcnt lgkmcnt(3)
	v_mfma_f32_32x32x16_bf16 v[18:33], v[236:239], v[8:11], v[18:33]
	ds_read2_b64 v[236:239], v218 offset0:76 offset1:78
	s_waitcnt lgkmcnt(3)
	v_mfma_f32_32x32x16_bf16 v[66:81], v[224:227], v[4:7], v[66:81]
	s_waitcnt lgkmcnt(2)
	v_mfma_f32_32x32x16_bf16 v[50:65], v[228:231], v[4:7], v[50:65]
	s_waitcnt lgkmcnt(1)
	v_mfma_f32_32x32x16_bf16 v[34:49], v[232:235], v[4:7], v[34:49]
	s_waitcnt lgkmcnt(0)
	v_mfma_f32_32x32x16_bf16 v[18:33], v[236:239], v[4:7], v[18:33]
	s_branch .LBB0_1236

; DI void attn_prompt_item(const Params& P, unsigned char* lds, int b, int head, int qb, float qkb2) {
;     ...
;     if (pending) ATT_PV(lds + pbuf * BUF, pp);
.LBB0_1240:
	s_or_b64 exec, exec, s[14:15]
	s_and_saveexec_b64 s[0:1], s[12:13]
	s_cbranch_execz .LBB0_1242
	v_mul_lo_u32 v2, v203, s60
	v_add_u32_e32 v2, 0, v2
	v_add3_u32 v2, v2, v201, v202
	v_add_u32_e32 v16, 0x4000, v2
	ds_read2_b64 v[224:227], v16 offset0:128 offset1:130
	v_add_u32_e32 v17, 0x5000, v2
	ds_read2_b64 v[228:231], v17 offset0:192 offset1:194
	v_add_u32_e32 v90, 0x6800, v2
	ds_read2_b64 v[232:235], v90 offset1:2
	v_add_u32_e32 v2, 0x7800, v2
	ds_read2_b64 v[236:239], v2 offset0:64 offset1:66
	s_waitcnt lgkmcnt(4)
	s_waitcnt lgkmcnt(3)
	v_mfma_f32_32x32x16_bf16 v[66:81], v[224:227], v[82:85], v[66:81]
	ds_read2_b64 v[224:227], v16 offset0:132 offset1:134
	s_waitcnt lgkmcnt(3)
	v_mfma_f32_32x32x16_bf16 v[50:65], v[228:231], v[82:85], v[50:65]
	ds_read2_b64 v[228:231], v17 offset0:196 offset1:198
	s_waitcnt lgkmcnt(3)
	v_mfma_f32_32x32x16_bf16 v[34:49], v[232:235], v[82:85], v[34:49]
	ds_read2_b64 v[232:235], v90 offset0:4 offset1:6
	s_waitcnt lgkmcnt(3)
	v_mfma_f32_32x32x16_bf16 v[18:33], v[236:239], v[82:85], v[18:33]
	ds_read2_b64 v[236:239], v2 offset0:68 offset1:70
	s_waitcnt lgkmcnt(3)
	v_mfma_f32_32x32x16_bf16 v[66:81], v[224:227], v[12:15], v[66:81]
	ds_read2_b64 v[224:227], v16 offset0:136 offset1:138
	s_waitcnt lgkmcnt(3)
	v_mfma_f32_32x32x16_bf16 v[50:65], v[228:231], v[12:15], v[50:65]
	ds_read2_b64 v[228:231], v17 offset0:200 offset1:202
	s_waitcnt lgkmcnt(3)
	v_mfma_f32_32x32x16_bf16 v[34:49], v[232:235], v[12:15], v[34:49]
	ds_read2_b64 v[232:235], v90 offset0:8 offset1:10
	s_waitcnt lgkmcnt(3)
	v_mfma_f32_32x32x16_bf16 v[18:33], v[236:239], v[12:15], v[18:33]
	ds_read2_b64 v[236:239], v2 offset0:72 offset1:74
	s_waitcnt lgkmcnt(3)
	v_mfma_f32_32x32x16_bf16 v[66:81], v[224:227], v[8:11], v[66:81]
	ds_read2_b64 v[224:227], v16 offset0:140 offset1:142
	s_waitcnt lgkmcnt(3)
	v_mfma_f32_32x32x16_bf16 v[50:65], v[228:231], v[8:11], v[50:65]
	ds_read2_b64 v[228:231], v17 offset0:204 offset1:206
	s_waitcnt lgkmcnt(3)
	v_mfma_f32_32x32x16_bf16 v[34:49], v[232:235], v[8:11], v[34:49]
	ds_read2_b64 v[232:235], v90 offset0:12 offset1:14
	s_waitcnt lgkmcnt(3)
	v_mfma_f32_32x32x16_bf16 v[18:33], v[236:239], v[8:11], v[18:33]
	ds_read2_b64 v[236:239], v2 offset0:76 offset1:78
	s_waitcnt lgkmcnt(3)
	v_mfma_f32_32x32x16_bf16 v[66:81], v[224:227], v[4:7], v[66:81]
	s_waitcnt lgkmcnt(2)
	v_mfma_f32_32x32x16_bf16 v[50:65], v[228:231], v[4:7], v[50:65]
	s_waitcnt lgkmcnt(1)
	v_mfma_f32_32x32x16_bf16 v[34:49], v[232:235], v[4:7], v[34:49]
	s_waitcnt lgkmcnt(0)
	v_mfma_f32_32x32x16_bf16 v[18:33], v[236:239], v[4:7], v[18:33]

; DI void attn_prompt_item(const Params& P, unsigned char* lds, int b, int head, int qb, float qkb2) {
;     ...
;     if (pending) ATT_PV(lds + pbuf * BUF, pp);
.LBB0_1318:
	s_or_b64 exec, exec, s[14:15]
	s_and_saveexec_b64 s[0:1], s[12:13]
	s_cbranch_execz .LBB0_1197
	v_mul_lo_u32 v2, v203, s60
	v_add_u32_e32 v2, 0, v2
	v_add3_u32 v2, v2, v201, v202
	v_add_u32_e32 v16, 0x4000, v2
	ds_read2_b64 v[224:227], v16 offset0:128 offset1:130
	v_add_u32_e32 v17, 0x5000, v2
	ds_read2_b64 v[228:231], v17 offset0:192 offset1:194
	v_add_u32_e32 v90, 0x6800, v2
	ds_read2_b64 v[232:235], v90 offset1:2
	v_add_u32_e32 v2, 0x7800, v2
	ds_read2_b64 v[236:239], v2 offset0:64 offset1:66
	s_waitcnt lgkmcnt(4)
	s_waitcnt lgkmcnt(3)
	v_mfma_f32_32x32x16_bf16 v[66:81], v[224:227], v[82:85], v[66:81]
	ds_read2_b64 v[224:227], v16 offset0:132 offset1:134
	s_waitcnt lgkmcnt(3)
	v_mfma_f32_32x32x16_bf16 v[50:65], v[228:231], v[82:85], v[50:65]
	ds_read2_b64 v[228:231], v17 offset0:196 offset1:198
	s_waitcnt lgkmcnt(3)
	v_mfma_f32_32x32x16_bf16 v[34:49], v[232:235], v[82:85], v[34:49]
	ds_read2_b64 v[232:235], v90 offset0:4 offset1:6
	s_waitcnt lgkmcnt(3)
	v_mfma_f32_32x32x16_bf16 v[18:33], v[236:239], v[82:85], v[18:33]
	ds_read2_b64 v[236:239], v2 offset0:68 offset1:70
	s_waitcnt lgkmcnt(3)
	v_mfma_f32_32x32x16_bf16 v[66:81], v[224:227], v[12:15], v[66:81]
	ds_read2_b64 v[224:227], v16 offset0:136 offset1:138
	s_waitcnt lgkmcnt(3)
	v_mfma_f32_32x32x16_bf16 v[50:65], v[228:231], v[12:15], v[50:65]
	ds_read2_b64 v[228:231], v17 offset0:200 offset1:202
	s_waitcnt lgkmcnt(3)
	v_mfma_f32_32x32x16_bf16 v[34:49], v[232:235], v[12:15], v[34:49]
	ds_read2_b64 v[232:235], v90 offset0:8 offset1:10
	s_waitcnt lgkmcnt(3)
	v_mfma_f32_32x32x16_bf16 v[18:33], v[236:239], v[12:15], v[18:33]
	ds_read2_b64 v[236:239], v2 offset0:72 offset1:74
	s_waitcnt lgkmcnt(3)
	v_mfma_f32_32x32x16_bf16 v[66:81], v[224:227], v[8:11], v[66:81]
	ds_read2_b64 v[224:227], v16 offset0:140 offset1:142
	s_waitcnt lgkmcnt(3)
	v_mfma_f32_32x32x16_bf16 v[50:65], v[228:231], v[8:11], v[50:65]
	ds_read2_b64 v[228:231], v17 offset0:204 offset1:206
	s_waitcnt lgkmcnt(3)
	v_mfma_f32_32x32x16_bf16 v[34:49], v[232:235], v[8:11], v[34:49]
	ds_read2_b64 v[232:235], v90 offset0:12 offset1:14
	s_waitcnt lgkmcnt(3)
	v_mfma_f32_32x32x16_bf16 v[18:33], v[236:239], v[8:11], v[18:33]
	ds_read2_b64 v[236:239], v2 offset0:76 offset1:78
	s_waitcnt lgkmcnt(3)
	v_mfma_f32_32x32x16_bf16 v[66:81], v[224:227], v[4:7], v[66:81]
	s_waitcnt lgkmcnt(2)
	v_mfma_f32_32x32x16_bf16 v[50:65], v[228:231], v[4:7], v[50:65]
	s_waitcnt lgkmcnt(1)
	v_mfma_f32_32x32x16_bf16 v[34:49], v[232:235], v[4:7], v[34:49]
	s_waitcnt lgkmcnt(0)
	v_mfma_f32_32x32x16_bf16 v[18:33], v[236:239], v[4:7], v[18:33]
	s_branch .LBB0_1197

; #define MFMA(a, b, c) __builtin_amdgcn_mfma_f32_32x32x16_bf16((a), (b), (c), 0, 0, 0)
; template <int NBW>
; DI void gemm_mainloop(f32x16 (&acc)[2][NBW], const bf16_t* A, size_t lda, int m0, const bf16_t* Bt, size_t ldb, int n0, int K, unsigned char* lds, bool pre = false, bool only_issue = false) {
;     ...
;     const int t = opaque_tid(), w = t >> 6, lane = t & 63, r = lane & 31, hh = lane >> 5, wm = w >> 1, wn = w & 1;
;     const int drow = w * 8 + (lane >> 3);
;     const int lchunk = (lane & 7) ^ ((drow >> 1) & 7);
;     const bf16_t* ap = A + (size_t)(m0 + drow) * lda + lchunk * 8;
;     const bf16_t* bp = Bt + (size_t)n0 * ldb + lchunk * 8;
;     size_t bro[NBW];
; #pragma unroll
;     for (int j = 0; j < NBW; ++j) {
;         const int rho = 64 * j + drow; const int wnh = rho / (32 * NBW), wi = rho % (32 * NBW);
;         bro[j] = (size_t)(wnh * 32 * NBW + NBW * (wi & 31) + (wi >> 5)) * ldb;
;     }
;     unsigned char* ldst = lds + w * 1024 + lane * 16;
;     ...
;     if (!pre) GEMM_ISSUE(0, 0);
;     if (only_issue) return;
;     __syncthreads();
;     const int nk = K >> 6;
;     const int xr = (r >> 1) & 7;
;     int xo[4];
; #pragma unroll
;     for (int s = 0; s < 4; ++s) xo[s] = ((2 * s + hh) ^ xr) << 4;
;     const int aofs = (wm * 64 + r) * 128;
;     const int bofs = BOFF + (wn * 32 * NBW + r) * 128;
; #pragma unroll 1
;     for (int kt = 0; kt < nk; ++kt) {
;         const unsigned char* st = lds + (kt & 1) * STAGE;
; #pragma unroll
;         for (int s = 0; s < 4; ++s) {
;             if (s == 1 && kt + 1 < nk) GEMM_ISSUE(kt + 1, (kt + 1) & 1);
;             bf16x8 a[2], b[NBW];
; #pragma unroll
;             for (int mb = 0; mb < 2; ++mb) a[mb] = *(const bf16x8*)(st + aofs + mb * 4096 + xo[s]);
; #pragma unroll
;             for (int nb = 0; nb < NBW; ++nb) b[nb] = *(const bf16x8*)(st + bofs + nb * 4096 + xo[s]);
; #pragma unroll
;             for (int mb = 0; mb < 2; ++mb)
; #pragma unroll
;                 for (int nb = 0; nb < NBW; ++nb) acc[mb][nb] = MFMA(a[mb], b[nb], acc[mb][nb]);
;         }
;         __syncthreads();
; DI void phase_p4(const Params& P, unsigned char* lds) {
;     ...
;         f32x16 a1[2][2], a2[2][2];
; #pragma unroll
;         for (int a = 0; a < 2; ++a)
; #pragma unroll
;             for (int b = 0; b < 2; ++b) { a1[a][b] = zero16(); a2[a][b] = zero16(); }
.LBB0_1398:
	v_and_b32_e32 v10, 31, v4
	v_lshrrev_b32_e32 v12, 6, v4
	v_lshrrev_b32_e32 v13, 1, v4
	v_bfe_u32 v14, v4, 1, 3
	v_lshlrev_b32_e32 v4, 7, v4
	v_and_b32_e32 v62, 0x2f80, v4
	v_add_u32_e32 v4, s65, v8
	v_add3_u32 v4, v4, v5, s78
	v_ashrrev_i32_e32 v5, 31, v4
	v_lshlrev_b64 v[4:5], 11, v[4:5]
	v_readlane_b32 s76, v223, 0
	v_or_b32_e32 v4, v4, v134
	v_readlane_b32 s77, v223, 1
	v_lshrrev_b32_e32 v11, 5, v9
	v_lshrrev_b32_e32 v9, 3, v9
	v_lshl_add_u64 v[50:51], s[76:77], 0, v[4:5]
	v_lshlrev_b16_e32 v4, 3, v12
	v_or_b32_e32 v8, v4, v9
	v_sub_u16_e32 v2, v8, v2
	v_and_b32_e32 v2, 31, v2
	v_lshl_add_u32 v4, v2, 1, v6
	v_sub_u16_e32 v2, v8, v3
	v_and_b32_e32 v2, 31, v2
	v_lshl_add_u32 v2, v2, 1, v7
	v_ashrrev_i32_e32 v3, 31, v2
	v_ashrrev_i32_e32 v5, 31, v4
	v_lshlrev_b64 v[2:3], 11, v[2:3]
	v_bitop3_b32 v15, v11, v13, 7 bitop3:0x78
	v_lshlrev_b64 v[4:5], 11, v[4:5]
	v_lshl_add_u64 v[2:3], v[2:3], 0, s[72:73]
	v_lshlrev_b32_e32 v57, 4, v15
	v_bitop3_b32 v15, v11, v14, 2 bitop3:0x36
	v_lshl_add_u64 v[4:5], v[4:5], 0, s[72:73]
	v_lshl_add_u64 v[2:3], v[2:3], 0, v[134:135]
	v_lshlrev_b32_e32 v58, 4, v15
	v_bitop3_b32 v15, v11, v14, 4 bitop3:0x36
	v_bitop3_b32 v11, v11, v14, 6 bitop3:0x36
	v_and_or_b32 v10, v13, s79, v10
	v_lshl_add_u64 v[4:5], v[4:5], 0, v[134:135]
	v_lshl_add_u64 v[54:55], s[8:9], 0, v[2:3]
	v_mov_b32_e32 v2, 0
	v_lshlrev_b32_e32 v59, 4, v15
	v_lshlrev_b32_e32 v60, 4, v11
	v_lshlrev_b32_e32 v61, 7, v10
	v_lshl_add_u64 v[52:53], s[8:9], 0, v[4:5]
	s_mov_b64 s[76:77], 0
	s_mov_b32 s67, 0x10000
	v_mov_b32_e32 v3, v2
	v_mov_b32_e32 v4, v2
	v_mov_b32_e32 v5, v2
	v_mov_b32_e32 v6, v2
	v_mov_b32_e32 v7, v2
	v_mov_b32_e32 v8, v2
	v_mov_b32_e32 v9, v2
	v_mov_b32_e32 v10, v2
	v_mov_b32_e32 v11, v2
	v_mov_b32_e32 v12, v2
	v_mov_b32_e32 v13, v2
	v_mov_b32_e32 v14, v2
	v_mov_b32_e32 v15, v2
	v_mov_b32_e32 v16, v2
	v_mov_b32_e32 v17, v2
	v_mov_b32_e32 v18, v2
	v_mov_b32_e32 v19, v2
	v_mov_b32_e32 v20, v2
	v_mov_b32_e32 v21, v2
	v_mov_b32_e32 v22, v2
	v_mov_b32_e32 v23, v2
	v_mov_b32_e32 v24, v2
	v_mov_b32_e32 v25, v2
	v_mov_b32_e32 v26, v2
	v_mov_b32_e32 v27, v2
	v_mov_b32_e32 v28, v2
	v_mov_b32_e32 v29, v2
	v_mov_b32_e32 v30, v2
	v_mov_b32_e32 v31, v2
	v_mov_b32_e32 v32, v2
	v_mov_b32_e32 v33, v2
	v_mov_b32_e32 v34, v2
	v_mov_b32_e32 v35, v2
	v_mov_b32_e32 v36, v2
	v_mov_b32_e32 v37, v2
	v_mov_b32_e32 v38, v2
	v_mov_b32_e32 v39, v2
	v_mov_b32_e32 v40, v2
	v_mov_b32_e32 v41, v2
	v_mov_b32_e32 v42, v2
	v_mov_b32_e32 v43, v2
	v_mov_b32_e32 v44, v2
	v_mov_b32_e32 v45, v2
	v_mov_b32_e32 v46, v2
	v_mov_b32_e32 v47, v2
	v_mov_b32_e32 v48, v2
	v_mov_b32_e32 v49, v2
	v_mov_b32_e32 v66, v2
	v_mov_b32_e32 v67, v2
	v_mov_b32_e32 v68, v2
	v_mov_b32_e32 v69, v2
	v_mov_b32_e32 v70, v2
	v_mov_b32_e32 v71, v2
	v_mov_b32_e32 v72, v2
	v_mov_b32_e32 v73, v2
	v_mov_b32_e32 v74, v2
	v_mov_b32_e32 v75, v2
	v_mov_b32_e32 v76, v2
	v_mov_b32_e32 v77, v2
	v_mov_b32_e32 v78, v2
	v_mov_b32_e32 v79, v2
	v_mov_b32_e32 v80, v2
	v_mov_b32_e32 v81, v2
	s_waitcnt vmcnt(0) lgkmcnt(0)
	s_barrier
	v_mov_b32_e32 v63, v61
	v_mov_b32_e32 v64, v62
	s_add_u32 s76, s76, 0x80
	s_addc_u32 s77, s77, 0
	s_add_i32 s67, s67, 0x10000
	v_add_u32_e32 v65, v63, v57
	v_add_u32_e32 v88, v64, v57
	ds_read_b128 v[240:243], v65
	ds_read_b128 v[248:251], v88 offset:32768
	ds_read_b128 v[244:247], v65 offset:4096
	ds_read_b128 v[252:255], v88 offset:36864
.Lp4a_kloop:
	s_waitcnt lgkmcnt(2)
	v_mfma_f32_32x32x16_bf16 v[66:81], v[240:243], v[248:251], v[66:81]
	v_add_u32_e32 v65, v63, v58
	v_add_u32_e32 v88, v64, v58
	ds_read_b128 v[224:227], v65
	s_waitcnt lgkmcnt(2)
	v_mfma_f32_32x32x16_bf16 v[18:33], v[244:247], v[248:251], v[18:33]
	ds_read_b128 v[232:235], v88 offset:32768
	s_waitcnt lgkmcnt(2)
	v_mfma_f32_32x32x16_bf16 v[34:49], v[240:243], v[252:255], v[34:49]
	ds_read_b128 v[228:231], v65 offset:4096
	v_mfma_f32_32x32x16_bf16 v[2:17], v[244:247], v[252:255], v[2:17]
	ds_read_b128 v[236:239], v88 offset:36864
	s_waitcnt lgkmcnt(2)
	v_mfma_f32_32x32x16_bf16 v[66:81], v[224:227], v[232:235], v[66:81]
	v_add_u32_e32 v65, v63, v59
	v_add_u32_e32 v88, v64, v59
	ds_read_b128 v[240:243], v65
	s_waitcnt lgkmcnt(2)
	v_mfma_f32_32x32x16_bf16 v[18:33], v[228:231], v[232:235], v[18:33]
	ds_read_b128 v[248:251], v88 offset:32768
	s_waitcnt lgkmcnt(2)
	v_mfma_f32_32x32x16_bf16 v[34:49], v[224:227], v[236:239], v[34:49]
	ds_read_b128 v[244:247], v65 offset:4096
	v_mfma_f32_32x32x16_bf16 v[2:17], v[228:231], v[236:239], v[2:17]
	ds_read_b128 v[252:255], v88 offset:36864
	s_waitcnt lgkmcnt(2)
	v_mfma_f32_32x32x16_bf16 v[66:81], v[240:243], v[248:251], v[66:81]
	v_add_u32_e32 v65, v63, v60
	v_add_u32_e32 v88, v64, v60
	ds_read_b128 v[224:227], v65
	s_waitcnt lgkmcnt(2)
	v_mfma_f32_32x32x16_bf16 v[18:33], v[244:247], v[248:251], v[18:33]
	ds_read_b128 v[232:235], v88 offset:32768
	s_waitcnt lgkmcnt(2)
	v_mfma_f32_32x32x16_bf16 v[34:49], v[240:243], v[252:255], v[34:49]
	ds_read_b128 v[228:231], v65 offset:4096
	v_mfma_f32_32x32x16_bf16 v[2:17], v[244:247], v[252:255], v[2:17]
	ds_read_b128 v[236:239], v88 offset:36864
	v_xor_b32_e32 v63, 0x10000, v63
	v_xor_b32_e32 v64, 0x10000, v64
	s_waitcnt vmcnt(0) lgkmcnt(0)
	s_barrier
	s_cmp_eq_u32 s76, 0x800
	s_cbranch_scc1 .Lp4a_klast
	s_cmp_eq_u32 s76, 0x780
	s_cbranch_scc1 .Lp4a_knodma
	v_mfma_f32_32x32x16_bf16 v[66:81], v[224:227], v[232:235], v[66:81]
	v_add_u32_e32 v65, v63, v57
	v_add_u32_e32 v88, v64, v57
	ds_read_b128 v[240:243], v65
	s_and_b32 s71, s67, 0x10000
	v_add_u32_e32 v86, s71, v56
	v_lshl_add_u64 v[84:85], v[50:51], 0, s[76:77]
	s_nop 0
	v_readfirstlane_b32 s71, v86
	s_mov_b64 s[86:87], 0xea81080
	v_lshl_add_u64 v[86:87], v[84:85], 0, s[86:87]
	s_mov_b32 m0, s71
	s_nop 0
	global_load_lds_dwordx4 v[86:87], off
	v_mfma_f32_32x32x16_bf16 v[18:33], v[228:231], v[232:235], v[18:33]
	ds_read_b128 v[248:251], v88 offset:32768
	s_mov_b64 s[86:87], 0xeaa1080
	v_lshl_add_u64 v[86:87], v[84:85], 0, s[86:87]
	s_add_i32 m0, s71, 0x2000
	s_nop 0
	global_load_lds_dwordx4 v[86:87], off
	s_mov_b64 s[86:87], 0xeac1080
	v_lshl_add_u64 v[86:87], v[84:85], 0, s[86:87]
	s_add_i32 m0, s71, 0x4000
	s_nop 0
	global_load_lds_dwordx4 v[86:87], off
	v_mfma_f32_32x32x16_bf16 v[34:49], v[224:227], v[236:239], v[34:49]
	ds_read_b128 v[244:247], v65 offset:4096
	s_mov_b64 s[86:87], 0xeae1080
	v_lshl_add_u64 v[86:87], v[84:85], 0, s[86:87]
	s_add_i32 m0, s71, 0x6000
	s_nop 0
	global_load_lds_dwordx4 v[86:87], off
	v_mfma_f32_32x32x16_bf16 v[2:17], v[228:231], v[236:239], v[2:17]
	ds_read_b128 v[252:255], v88 offset:36864
	v_lshl_add_u64 v[86:87], v[52:53], 0, s[76:77]
	s_add_i32 m0, s71, 0x8000
	s_nop 0
	global_load_lds_dwordx4 v[86:87], off
	v_lshl_add_u64 v[86:87], v[54:55], 0, s[76:77]
	s_add_i32 m0, s71, 0xa000
	s_nop 0
	global_load_lds_dwordx4 v[86:87], off
	s_add_u32 s76, s76, 0x80
	s_addc_u32 s77, s77, 0
	s_add_i32 s67, s67, 0x10000
	s_branch .Lp4a_kloop
; #define MFMA(a, b, c) __builtin_amdgcn_mfma_f32_32x32x16_bf16((a), (b), (c), 0, 0, 0)
; DI int opaque_tid() { int t = threadIdx.x; asm volatile("" : "+v"(t)); return t; }
; #define GEMM_ISSUE(KT, ST) do { const int k1_ = (KT) << 6; unsigned char* d_ = ldst + (ST) * STAGE; \
;         _Pragma("unroll") for (int j_ = 0; j_ < 4; ++j_) dma16(ap + (size_t)(64 * j_) * lda + k1_, d_ + j_ * 8192); \
;         _Pragma("unroll") for (int j_ = 0; j_ < NBW; ++j_) dma16(bp + bro[j_] + k1_, d_ + BOFF + j_ * 8192); } while (0)
; template <int NBW>
; DI void gemm_mainloop(f32x16 (&acc)[2][NBW], const bf16_t* A, size_t lda, int m0, const bf16_t* Bt, size_t ldb, int n0, int K, unsigned char* lds, bool pre = false, bool only_issue = false) {
;     constexpr int STAGE = 65536, BOFF = 32768;
;     const int t = opaque_tid(), w = t >> 6, lane = t & 63, r = lane & 31, hh = lane >> 5, wm = w >> 1, wn = w & 1;
;     const int drow = w * 8 + (lane >> 3);
;     const int lchunk = (lane & 7) ^ ((drow >> 1) & 7);
;     const bf16_t* ap = A + (size_t)(m0 + drow) * lda + lchunk * 8;
;     const bf16_t* bp = Bt + (size_t)n0 * ldb + lchunk * 8;
;     size_t bro[NBW];
; #pragma unroll
;     for (int j = 0; j < NBW; ++j) {
;         const int rho = 64 * j + drow; const int wnh = rho / (32 * NBW), wi = rho % (32 * NBW);
;         bro[j] = (size_t)(wnh * 32 * NBW + NBW * (wi & 31) + (wi >> 5)) * ldb;
;     }
;     unsigned char* ldst = lds + w * 1024 + lane * 16;
;     ...
;     if (!pre) GEMM_ISSUE(0, 0);
;     ...
;     for (int kt = 0; kt < nk; ++kt) {
;         const unsigned char* st = lds + (kt & 1) * STAGE;
; #pragma unroll
;         for (int s = 0; s < 4; ++s) {
;             if (s == 1 && kt + 1 < nk) GEMM_ISSUE(kt + 1, (kt + 1) & 1);
;             bf16x8 a[2], b[NBW];
; #pragma unroll
;             for (int mb = 0; mb < 2; ++mb) a[mb] = *(const bf16x8*)(st + aofs + mb * 4096 + xo[s]);
; #pragma unroll
;             for (int nb = 0; nb < NBW; ++nb) b[nb] = *(const bf16x8*)(st + bofs + nb * 4096 + xo[s]);
; #pragma unroll
;             for (int mb = 0; mb < 2; ++mb)
; #pragma unroll
;                 for (int nb = 0; nb < NBW; ++nb) acc[mb][nb] = MFMA(a[mb], b[nb], acc[mb][nb]);
;         }
;         __syncthreads();
;     }
.Lp4a_knodma:
	v_mfma_f32_32x32x16_bf16 v[66:81], v[224:227], v[232:235], v[66:81]
	v_add_u32_e32 v65, v63, v57
	v_add_u32_e32 v88, v64, v57
	ds_read_b128 v[240:243], v65
	v_mfma_f32_32x32x16_bf16 v[18:33], v[228:231], v[232:235], v[18:33]
	ds_read_b128 v[248:251], v88 offset:32768
	v_mfma_f32_32x32x16_bf16 v[34:49], v[224:227], v[236:239], v[34:49]
	ds_read_b128 v[244:247], v65 offset:4096
	v_mfma_f32_32x32x16_bf16 v[2:17], v[228:231], v[236:239], v[2:17]
	ds_read_b128 v[252:255], v88 offset:36864
	s_add_u32 s76, s76, 0x80
	s_addc_u32 s77, s77, 0
	s_add_i32 s67, s67, 0x10000
	s_branch .Lp4a_kloop
.Lp4a_klast:
	v_mfma_f32_32x32x16_bf16 v[66:81], v[224:227], v[232:235], v[66:81]
	v_mfma_f32_32x32x16_bf16 v[18:33], v[228:231], v[232:235], v[18:33]
	v_mfma_f32_32x32x16_bf16 v[34:49], v[224:227], v[236:239], v[34:49]
	v_mfma_f32_32x32x16_bf16 v[2:17], v[228:231], v[236:239], v[2:17]
	s_mov_b32 s71, 0x10000
	s_mov_b64 s[86:87], 0xeae1080
.LBB0_1402:
	v_mov_b32_e32 v60, v1
	s_add_u32 s76, s38, s72
	v_ashrrev_i32_e32 v61, 6, v60
	v_lshlrev_b32_e32 v63, 3, v61
	v_bfe_u32 v64, v60, 3, 3
	v_ashrrev_i32_e32 v52, 31, v60
	v_or_b32_e32 v54, v63, v64
	v_lshrrev_b32_e32 v52, 26, v52
	v_add_u32_e32 v52, v54, v52
	v_lshrrev_b32_e32 v53, 6, v52
	v_mul_i32_i24_e32 v53, 64, v53
	v_sub_u32_e32 v53, v54, v53
	v_and_b32_e32 v58, 63, v60
	v_lshrrev_b32_e32 v65, 1, v54
	v_add_u32_e32 v50, s66, v54
	v_and_b32_e32 v52, 0xffffffc0, v52
	v_lshlrev_b32_e32 v55, 1, v53
	v_ashrrev_i32_e32 v53, 5, v53
	v_xor_b32_e32 v56, v65, v60
	v_ashrrev_i32_e32 v51, 31, v50
	v_and_b32_e32 v55, 62, v55
	v_add_u32_e32 v82, v53, v52
	v_add_u32_e32 v54, 64, v54
	v_lshlrev_b32_e32 v59, 10, v61
	v_lshlrev_b32_e32 v58, 4, v58
	v_lshlrev_b64 v[50:51], 11, v[50:51]
	v_add_u32_e32 v52, v82, v55
	v_ashrrev_i32_e32 v55, 31, v54
	v_lshlrev_b32_e32 v56, 4, v56
	v_add3_u32 v141, 0, v59, v58
	v_lshrrev_b32_e32 v55, 26, v55
	v_lshl_add_u64 v[50:51], s[4:5], 0, v[50:51]
	v_and_b32_e32 v134, 0x70, v56
	v_readfirstlane_b32 s67, v141
	v_add_u32_e32 v85, 0x2000, v141
	v_add_u32_e32 v55, v54, v55
	v_lshl_add_u64 v[50:51], v[50:51], 0, v[134:135]
	s_mov_b32 m0, s67
	v_readfirstlane_b32 s67, v85
	v_add_u32_e32 v85, 0x4000, v141
	v_lshrrev_b32_e32 v57, 6, v55
	global_load_lds_dwordx4 v[50:51], off
	s_nop 0
	s_cselect_b32 s98, 1, 0
	s_add_i32 m0, m0, 0xff80
	s_cmp_lg_u32 s98, 0
	global_load_lds_dwordx4 v[50:51], off offset:128
	s_nop 0
	v_lshl_add_u64 v[58:59], v[50:51], 0, s[12:13]
	s_mov_b32 m0, s67
	v_readfirstlane_b32 s67, v85
	v_mul_i32_i24_e32 v57, 64, v57
	global_load_lds_dwordx4 v[58:59], off
	s_nop 0
	s_cselect_b32 s98, 1, 0
	s_add_i32 m0, m0, 0xff80
	s_cmp_lg_u32 s98, 0
	global_load_lds_dwordx4 v[58:59], off offset:128
	s_nop 0
	v_lshl_add_u64 v[58:59], v[50:51], 0, s[14:15]
	s_mov_b32 m0, s67
	v_sub_u32_e32 v54, v54, v57
	global_load_lds_dwordx4 v[58:59], off
	s_nop 0
	s_cselect_b32 s98, 1, 0
	s_add_i32 m0, m0, 0xff80
	s_cmp_lg_u32 s98, 0
	global_load_lds_dwordx4 v[58:59], off offset:128
	s_nop 0
	v_add_u32_e32 v58, 0x6000, v141
	v_and_b32_e32 v55, 0xffffffc0, v55
	v_lshlrev_b32_e32 v57, 1, v54
	v_ashrrev_i32_e32 v54, 5, v54
	v_readfirstlane_b32 s67, v58
	s_addc_u32 s77, s39, s73
	v_ashrrev_i32_e32 v53, 31, v52
	v_and_b32_e32 v57, 62, v57
	v_add_u32_e32 v83, v54, v55
	v_lshl_add_u64 v[50:51], v[50:51], 0, s[16:17]
	s_mov_b32 m0, s67
	v_add_u32_e32 v58, 0x8000, v141
	v_add_u32_e32 v54, v83, v57
	v_lshl_add_u64 v[56:57], s[76:77], 0, v[134:135]
	global_load_lds_dwordx4 v[50:51], off
	s_nop 0
	s_cselect_b32 s98, 1, 0
	s_add_i32 m0, m0, 0xff80
	s_cmp_lg_u32 s98, 0
	global_load_lds_dwordx4 v[50:51], off offset:128
	s_nop 0
	v_lshlrev_b64 v[50:51], 11, v[52:53]
	v_readfirstlane_b32 s67, v58
	v_ashrrev_i32_e32 v55, 31, v54
	v_lshl_add_u64 v[50:51], v[56:57], 0, v[50:51]
	s_mov_b32 m0, s67
	v_add_u32_e32 v52, 0xa000, v141
	global_load_lds_dwordx4 v[50:51], off
	s_nop 0
	s_cselect_b32 s98, 1, 0
	s_add_i32 m0, m0, 0xff80
	s_cmp_lg_u32 s98, 0
	global_load_lds_dwordx4 v[50:51], off offset:128
	s_nop 0
	v_lshlrev_b64 v[50:51], 11, v[54:55]
	v_readfirstlane_b32 s67, v52
	v_lshl_add_u64 v[50:51], v[56:57], 0, v[50:51]
	s_mov_b32 m0, s67
	v_and_b32_e32 v62, 31, v60
	global_load_lds_dwordx4 v[50:51], off
	s_nop 0
	s_cselect_b32 s98, 1, 0
	s_add_i32 m0, m0, 0xff80
	s_cmp_lg_u32 s98, 0
	global_load_lds_dwordx4 v[50:51], off offset:128
	s_nop 0
	v_bfe_u32 v84, v60, 5, 1
	v_lshrrev_b32_e32 v50, 1, v60
	v_bitop3_b32 v52, v84, v50, 7 bitop3:0x78
	v_and_or_b32 v50, v50, s79, v62
	v_bfe_u32 v51, v60, 1, 3
	v_lshlrev_b32_e32 v151, 7, v50
	v_lshlrev_b32_e32 v50, 7, v60
	v_lshlrev_b32_e32 v143, 4, v52
	v_bitop3_b32 v52, v84, v51, 2 bitop3:0x36
	v_and_b32_e32 v153, 0x2f80, v50
	v_add_u32_e32 v50, s65, v64
	v_lshlrev_b32_e32 v145, 4, v52
	v_bitop3_b32 v52, v84, v51, 4 bitop3:0x36
	v_bitop3_b32 v51, v84, v51, 6 bitop3:0x36
	v_add3_u32 v50, v50, v63, s78
	v_lshlrev_b32_e32 v147, 4, v52
	v_lshlrev_b32_e32 v149, 4, v51
	v_ashrrev_i32_e32 v51, 31, v50
	v_bitop3_b32 v52, v65, 7, v60 bitop3:0x48
	v_lshlrev_b64 v[50:51], 11, v[50:51]
	v_lshlrev_b32_e32 v134, 4, v52
	v_readlane_b32 s76, v223, 0
	v_or_b32_e32 v50, v50, v134
	v_readlane_b32 s77, v223, 1
	s_mov_b32 s65, 0x10000
	s_waitcnt vmcnt(0) lgkmcnt(0)
; DI int opaque_tid() { int t = threadIdx.x; asm volatile("" : "+v"(t)); return t; }
; #define GEMM_ISSUE(KT, ST) do { const int k1_ = (KT) << 6; unsigned char* d_ = ldst + (ST) * STAGE; \
;         _Pragma("unroll") for (int j_ = 0; j_ < 4; ++j_) dma16(ap + (size_t)(64 * j_) * lda + k1_, d_ + j_ * 8192); \
;         _Pragma("unroll") for (int j_ = 0; j_ < NBW; ++j_) dma16(bp + bro[j_] + k1_, d_ + BOFF + j_ * 8192); } while (0)
; template <int NBW>
; DI void gemm_mainloop(f32x16 (&acc)[2][NBW], const bf16_t* A, size_t lda, int m0, const bf16_t* Bt, size_t ldb, int n0, int K, unsigned char* lds, bool pre = false, bool only_issue = false) {
;     ...
;     const int t = opaque_tid(), w = t >> 6, lane = t & 63, r = lane & 31, hh = lane >> 5, wm = w >> 1, wn = w & 1;
;     const int drow = w * 8 + (lane >> 3);
;     const int lchunk = (lane & 7) ^ ((drow >> 1) & 7);
;     const bf16_t* ap = A + (size_t)(m0 + drow) * lda + lchunk * 8;
;     const bf16_t* bp = Bt + (size_t)n0 * ldb + lchunk * 8;
;     size_t bro[NBW];
; #pragma unroll
;     for (int j = 0; j < NBW; ++j) {
;         const int rho = 64 * j + drow; const int wnh = rho / (32 * NBW), wi = rho % (32 * NBW);
;         bro[j] = (size_t)(wnh * 32 * NBW + NBW * (wi & 31) + (wi >> 5)) * ldb;
;     }
;     unsigned char* ldst = lds + w * 1024 + lane * 16;
;     ...
;     if (!pre) GEMM_ISSUE(0, 0);
;     if (only_issue) return;
;     __syncthreads();
;     const int nk = K >> 6;
;     const int xr = (r >> 1) & 7;
;     int xo[4];
; #pragma unroll
;     for (int s = 0; s < 4; ++s) xo[s] = ((2 * s + hh) ^ xr) << 4;
;     const int aofs = (wm * 64 + r) * 128;
;     const int bofs = BOFF + (wn * 32 * NBW + r) * 128;
	v_lshl_add_u64 v[168:169], s[76:77], 0, v[50:51]
	v_lshlrev_b16_e32 v50, 3, v61
	v_or_b32_e32 v50, v50, v64
	v_and_b32_e32 v50, 31, v50
	v_lshlrev_b32_e32 v52, 1, v50
	v_add_u32_e32 v50, v82, v52
	v_ashrrev_i32_e32 v51, 31, v50
	v_lshlrev_b64 v[50:51], 11, v[50:51]
	v_lshl_add_u64 v[50:51], v[50:51], 0, s[72:73]
	v_lshl_add_u64 v[50:51], v[50:51], 0, v[134:135]
	v_lshl_add_u64 v[170:171], s[10:11], 0, v[50:51]
	v_add_u32_e32 v50, v83, v52
	v_ashrrev_i32_e32 v51, 31, v50
	v_lshlrev_b64 v[50:51], 11, v[50:51]
	v_lshl_add_u64 v[50:51], v[50:51], 0, s[72:73]
	v_lshl_add_u64 v[50:51], v[50:51], 0, v[134:135]
	v_lshl_add_u64 v[172:173], s[10:11], 0, v[50:51]
	v_mov_b32_e32 v50, 0
	s_mov_b64 s[72:73], 0
	v_mov_b32_e32 v51, v50
	v_mov_b32_e32 v52, v50
	v_mov_b32_e32 v53, v50
	v_mov_b32_e32 v54, v50
	v_mov_b32_e32 v55, v50
	v_mov_b32_e32 v56, v50
	v_mov_b32_e32 v57, v50
	v_mov_b32_e32 v58, v50
	v_mov_b32_e32 v59, v50
	v_mov_b32_e32 v60, v50
	v_mov_b32_e32 v61, v50
	v_mov_b32_e32 v62, v50
	v_mov_b32_e32 v63, v50
	v_mov_b32_e32 v64, v50
	v_mov_b32_e32 v65, v50
	v_mov_b32_e32 v82, v50
	v_mov_b32_e32 v83, v50
	v_mov_b32_e32 v84, v50
	v_mov_b32_e32 v85, v50
	v_mov_b32_e32 v86, v50
	v_mov_b32_e32 v87, v50
	v_mov_b32_e32 v88, v50
	v_mov_b32_e32 v89, v50
	v_mov_b32_e32 v90, v50
	v_mov_b32_e32 v91, v50
	v_mov_b32_e32 v92, v50
	v_mov_b32_e32 v93, v50
	v_mov_b32_e32 v94, v50
	v_mov_b32_e32 v95, v50
	v_mov_b32_e32 v96, v50
	v_mov_b32_e32 v97, v50
	v_mov_b32_e32 v98, v50
	v_mov_b32_e32 v99, v50
	v_mov_b32_e32 v100, v50
	v_mov_b32_e32 v101, v50
	v_mov_b32_e32 v102, v50
	v_mov_b32_e32 v103, v50
	v_mov_b32_e32 v104, v50
	v_mov_b32_e32 v105, v50
	v_mov_b32_e32 v106, v50
	v_mov_b32_e32 v107, v50
	v_mov_b32_e32 v108, v50
	v_mov_b32_e32 v109, v50
	v_mov_b32_e32 v110, v50
	v_mov_b32_e32 v111, v50
	v_mov_b32_e32 v112, v50
	v_mov_b32_e32 v113, v50
	v_mov_b32_e32 v114, v50
	v_mov_b32_e32 v115, v50
	v_mov_b32_e32 v116, v50
	v_mov_b32_e32 v117, v50
	v_mov_b32_e32 v118, v50
	v_mov_b32_e32 v119, v50
	v_mov_b32_e32 v120, v50
	v_mov_b32_e32 v121, v50
	v_mov_b32_e32 v122, v50
	v_mov_b32_e32 v123, v50
	v_mov_b32_e32 v124, v50
	v_mov_b32_e32 v125, v50
	v_mov_b32_e32 v126, v50
	v_mov_b32_e32 v127, v50
	v_mov_b32_e32 v128, v50
	v_mov_b32_e32 v129, v50
	s_barrier
	v_mov_b32_e32 v134, v151
	v_mov_b32_e32 v155, v153
	s_add_u32 s72, s72, 0x80
	s_addc_u32 s73, s73, 0
	s_add_i32 s65, s65, 0x10000
	v_add_u32_e32 v157, v134, v143
	v_add_u32_e32 v159, v155, v143
	ds_read_b128 v[240:243], v157
	ds_read_b128 v[248:251], v159 offset:32768
	ds_read_b128 v[244:247], v157 offset:4096
	ds_read_b128 v[252:255], v159 offset:36864
; #define MFMA(a, b, c) __builtin_amdgcn_mfma_f32_32x32x16_bf16((a), (b), (c), 0, 0, 0)
; #define GEMM_ISSUE(KT, ST) do { const int k1_ = (KT) << 6; unsigned char* d_ = ldst + (ST) * STAGE; \
;         _Pragma("unroll") for (int j_ = 0; j_ < 4; ++j_) dma16(ap + (size_t)(64 * j_) * lda + k1_, d_ + j_ * 8192); \
;         _Pragma("unroll") for (int j_ = 0; j_ < NBW; ++j_) dma16(bp + bro[j_] + k1_, d_ + BOFF + j_ * 8192); } while (0)
; template <int NBW>
; DI void gemm_mainloop(f32x16 (&acc)[2][NBW], const bf16_t* A, size_t lda, int m0, const bf16_t* Bt, size_t ldb, int n0, int K, unsigned char* lds, bool pre = false, bool only_issue = false) {
;     ...
;     for (int kt = 0; kt < nk; ++kt) {
;         const unsigned char* st = lds + (kt & 1) * STAGE;
; #pragma unroll
;         for (int s = 0; s < 4; ++s) {
;             if (s == 1 && kt + 1 < nk) GEMM_ISSUE(kt + 1, (kt + 1) & 1);
;             bf16x8 a[2], b[NBW];
; #pragma unroll
;             for (int mb = 0; mb < 2; ++mb) a[mb] = *(const bf16x8*)(st + aofs + mb * 4096 + xo[s]);
; #pragma unroll
;             for (int nb = 0; nb < NBW; ++nb) b[nb] = *(const bf16x8*)(st + bofs + nb * 4096 + xo[s]);
; #pragma unroll
;             for (int mb = 0; mb < 2; ++mb)
; #pragma unroll
;                 for (int nb = 0; nb < NBW; ++nb) acc[mb][nb] = MFMA(a[mb], b[nb], acc[mb][nb]);
;         }
;         __syncthreads();
;     }
.Lp4b_kloop:
	s_waitcnt lgkmcnt(2)
	v_mfma_f32_32x32x16_bf16 v[114:129], v[240:243], v[248:251], v[114:129]
	v_add_u32_e32 v157, v134, v145
	v_add_u32_e32 v159, v155, v145
	ds_read_b128 v[224:227], v157
	s_waitcnt lgkmcnt(2)
	v_mfma_f32_32x32x16_bf16 v[82:97], v[244:247], v[248:251], v[82:97]
	ds_read_b128 v[232:235], v159 offset:32768
	s_waitcnt lgkmcnt(2)
	v_mfma_f32_32x32x16_bf16 v[98:113], v[240:243], v[252:255], v[98:113]
	ds_read_b128 v[228:231], v157 offset:4096
	v_mfma_f32_32x32x16_bf16 v[50:65], v[244:247], v[252:255], v[50:65]
	ds_read_b128 v[236:239], v159 offset:36864
	s_waitcnt lgkmcnt(2)
	v_mfma_f32_32x32x16_bf16 v[114:129], v[224:227], v[232:235], v[114:129]
	v_add_u32_e32 v157, v134, v147
	v_add_u32_e32 v159, v155, v147
	ds_read_b128 v[240:243], v157
	s_waitcnt lgkmcnt(2)
	v_mfma_f32_32x32x16_bf16 v[82:97], v[228:231], v[232:235], v[82:97]
	ds_read_b128 v[248:251], v159 offset:32768
	s_waitcnt lgkmcnt(2)
	v_mfma_f32_32x32x16_bf16 v[98:113], v[224:227], v[236:239], v[98:113]
	ds_read_b128 v[244:247], v157 offset:4096
	v_mfma_f32_32x32x16_bf16 v[50:65], v[228:231], v[236:239], v[50:65]
	ds_read_b128 v[252:255], v159 offset:36864
	s_waitcnt lgkmcnt(2)
	v_mfma_f32_32x32x16_bf16 v[114:129], v[240:243], v[248:251], v[114:129]
	v_add_u32_e32 v157, v134, v149
	v_add_u32_e32 v159, v155, v149
	ds_read_b128 v[224:227], v157
	s_waitcnt lgkmcnt(2)
	v_mfma_f32_32x32x16_bf16 v[82:97], v[244:247], v[248:251], v[82:97]
	ds_read_b128 v[232:235], v159 offset:32768
	s_waitcnt lgkmcnt(2)
	v_mfma_f32_32x32x16_bf16 v[98:113], v[240:243], v[252:255], v[98:113]
	ds_read_b128 v[228:231], v157 offset:4096
	v_mfma_f32_32x32x16_bf16 v[50:65], v[244:247], v[252:255], v[50:65]
	ds_read_b128 v[236:239], v159 offset:36864
	v_xor_b32_e32 v134, 0x10000, v134
	v_xor_b32_e32 v155, 0x10000, v155
	s_waitcnt vmcnt(0) lgkmcnt(0)
	s_barrier
	s_cmp_eq_u32 s72, 0x800
	s_cbranch_scc1 .Lp4b_klast
	s_cmp_eq_u32 s72, 0x780
	s_cbranch_scc1 .Lp4b_knodma
	v_mfma_f32_32x32x16_bf16 v[114:129], v[224:227], v[232:235], v[114:129]
	v_add_u32_e32 v157, v134, v143
	v_add_u32_e32 v159, v155, v143
	ds_read_b128 v[240:243], v157
	s_and_b32 s67, s65, 0x10000
	v_add_u32_e32 v176, s67, v141
	v_lshl_add_u64 v[174:175], v[168:169], 0, s[72:73]
	s_nop 0
	v_readfirstlane_b32 s67, v176
	s_mov_b64 s[76:77], 0x12c01080
	v_lshl_add_u64 v[176:177], v[174:175], 0, s[76:77]
	s_mov_b32 m0, s67
	s_nop 0
	global_load_lds_dwordx4 v[176:177], off
	v_mfma_f32_32x32x16_bf16 v[82:97], v[228:231], v[232:235], v[82:97]
	ds_read_b128 v[248:251], v159 offset:32768
	s_mov_b64 s[76:77], 0x12c21080
	v_lshl_add_u64 v[176:177], v[174:175], 0, s[76:77]
	s_add_i32 m0, s67, 0x2000
	s_nop 0
	global_load_lds_dwordx4 v[176:177], off
	s_mov_b64 s[76:77], 0x12c41080
	v_lshl_add_u64 v[176:177], v[174:175], 0, s[76:77]
	s_add_i32 m0, s67, 0x4000
	s_nop 0
	global_load_lds_dwordx4 v[176:177], off
	v_mfma_f32_32x32x16_bf16 v[98:113], v[224:227], v[236:239], v[98:113]
	ds_read_b128 v[244:247], v157 offset:4096
	s_mov_b64 s[76:77], 0x12c61080
	v_lshl_add_u64 v[176:177], v[174:175], 0, s[76:77]
	s_add_i32 m0, s67, 0x6000
	s_nop 0
	global_load_lds_dwordx4 v[176:177], off
	v_mfma_f32_32x32x16_bf16 v[50:65], v[228:231], v[236:239], v[50:65]
	ds_read_b128 v[252:255], v159 offset:36864
	v_lshl_add_u64 v[176:177], v[170:171], 0, s[72:73]
	s_add_i32 m0, s67, 0x8000
	s_nop 0
	global_load_lds_dwordx4 v[176:177], off
	v_lshl_add_u64 v[176:177], v[172:173], 0, s[72:73]
	s_add_i32 m0, s67, 0xa000
	s_nop 0
	global_load_lds_dwordx4 v[176:177], off
	s_add_u32 s72, s72, 0x80
	s_addc_u32 s73, s73, 0
	s_add_i32 s65, s65, 0x10000
	s_branch .Lp4b_kloop
.Lp4b_knodma:
	v_mfma_f32_32x32x16_bf16 v[114:129], v[224:227], v[232:235], v[114:129]
	v_add_u32_e32 v157, v134, v143
	v_add_u32_e32 v159, v155, v143
	ds_read_b128 v[240:243], v157
	v_mfma_f32_32x32x16_bf16 v[82:97], v[228:231], v[232:235], v[82:97]
	ds_read_b128 v[248:251], v159 offset:32768
	v_mfma_f32_32x32x16_bf16 v[98:113], v[224:227], v[236:239], v[98:113]
	ds_read_b128 v[244:247], v157 offset:4096
	v_mfma_f32_32x32x16_bf16 v[50:65], v[228:231], v[236:239], v[50:65]
	ds_read_b128 v[252:255], v159 offset:36864
	s_add_u32 s72, s72, 0x80
	s_addc_u32 s73, s73, 0
	s_add_i32 s65, s65, 0x10000
	s_branch .Lp4b_kloop
.Lp4b_klast:
	v_mfma_f32_32x32x16_bf16 v[114:129], v[224:227], v[232:235], v[114:129]
	v_mfma_f32_32x32x16_bf16 v[82:97], v[228:231], v[232:235], v[82:97]
	v_mfma_f32_32x32x16_bf16 v[98:113], v[224:227], v[236:239], v[98:113]
	v_mfma_f32_32x32x16_bf16 v[50:65], v[228:231], v[236:239], v[50:65]
	s_mov_b32 s67, 0x10000
	s_mov_b64 s[76:77], 0x12c61080

; DI int opaque_tid() { int t = threadIdx.x; asm volatile("" : "+v"(t)); return t; }
; #define GEMM_ISSUE(KT, ST) do { const int k1_ = (KT) << 6; unsigned char* d_ = ldst + (ST) * STAGE; \
;         _Pragma("unroll") for (int j_ = 0; j_ < 4; ++j_) dma16(ap + (size_t)(64 * j_) * lda + k1_, d_ + j_ * 8192); \
;         _Pragma("unroll") for (int j_ = 0; j_ < NBW; ++j_) dma16(bp + bro[j_] + k1_, d_ + BOFF + j_ * 8192); } while (0)
; template <int NBW>
; DI void gemm_mainloop(f32x16 (&acc)[2][NBW], const bf16_t* A, size_t lda, int m0, const bf16_t* Bt, size_t ldb, int n0, int K, unsigned char* lds, bool pre = false, bool only_issue = false) {
;     ...
;     const int t = opaque_tid(), w = t >> 6, lane = t & 63, r = lane & 31, hh = lane >> 5, wm = w >> 1, wn = w & 1;
;     const int drow = w * 8 + (lane >> 3);
;     const int lchunk = (lane & 7) ^ ((drow >> 1) & 7);
;     const bf16_t* ap = A + (size_t)(m0 + drow) * lda + lchunk * 8;
;     const bf16_t* bp = Bt + (size_t)n0 * ldb + lchunk * 8;
;     size_t bro[NBW];
; #pragma unroll
;     for (int j = 0; j < NBW; ++j) {
;         const int rho = 64 * j + drow; const int wnh = rho / (32 * NBW), wi = rho % (32 * NBW);
;         bro[j] = (size_t)(wnh * 32 * NBW + NBW * (wi & 31) + (wi >> 5)) * ldb;
;     }
;     unsigned char* ldst = lds + w * 1024 + lane * 16;
;     ...
;     if (!pre) GEMM_ISSUE(0, 0);
;     if (only_issue) return;
;     __syncthreads();
;     const int nk = K >> 6;
;     const int xr = (r >> 1) & 7;
;     int xo[4];
; #pragma unroll
;     for (int s = 0; s < 4; ++s) xo[s] = ((2 * s + hh) ^ xr) << 4;
;     const int aofs = (wm * 64 + r) * 128;
;     const int bofs = BOFF + (wn * 32 * NBW + r) * 128;
.LBB0_1487:
	v_and_b32_e32 v15, 31, v13
	v_lshlrev_b32_e32 v11, 7, v11
	v_and_or_b32 v11, v11, s36, v15
	v_lshrrev_b32_e32 v17, 6, v13
	s_waitcnt vmcnt(0)
	v_lshlrev_b32_e32 v146, 7, v11
	v_add_u32_e32 v11, s25, v12
	v_lshrrev_b32_e32 v16, 5, v14
	v_lshrrev_b32_e32 v14, 3, v14
	v_add3_u32 v12, v11, v6, s36
	v_lshlrev_b16_e32 v6, 3, v17
	v_or_b32_e32 v11, v6, v14
	v_sub_u16_e32 v2, v11, v2
	v_and_b32_e32 v2, 31, v2
	v_lshl_add_u32 v6, v2, 2, v7
	v_sub_u16_e32 v2, v11, v3
	v_and_b32_e32 v2, 31, v2
	v_lshl_add_u32 v2, v2, 2, v8
	v_ashrrev_i32_e32 v3, 31, v2
	v_lshlrev_b64 v[2:3], 11, v[2:3]
	v_lshl_add_u64 v[2:3], v[2:3], 0, s[22:23]
	v_lshl_add_u64 v[2:3], v[2:3], 0, v[164:165]
	v_lshl_add_u64 v[134:135], s[6:7], 0, v[2:3]
	v_sub_u16_e32 v2, v11, v4
	v_and_b32_e32 v2, 31, v2
	v_lshl_add_u32 v2, v2, 2, v9
	v_ashrrev_i32_e32 v3, 31, v2
	v_lshlrev_b64 v[2:3], 11, v[2:3]
	v_lshl_add_u64 v[2:3], v[2:3], 0, s[22:23]
	v_lshl_add_u64 v[2:3], v[2:3], 0, v[164:165]
	v_lshrrev_b32_e32 v18, 1, v13
	v_lshl_add_u64 v[136:137], s[6:7], 0, v[2:3]
	v_sub_u16_e32 v2, v11, v5
	v_bfe_u32 v13, v13, 1, 3
	v_bitop3_b32 v19, v16, v18, 7 bitop3:0x78
	v_and_b32_e32 v2, 31, v2
	v_lshlrev_b32_e32 v141, 4, v19
	v_bitop3_b32 v19, v16, v13, 2 bitop3:0x36
	v_lshl_add_u32 v2, v2, 2, v10
	v_lshlrev_b32_e32 v142, 4, v19
	v_bitop3_b32 v19, v16, v13, 4 bitop3:0x36
	v_bitop3_b32 v13, v16, v13, 6 bitop3:0x36
	v_ashrrev_i32_e32 v3, 31, v2
	v_lshlrev_b32_e32 v144, 4, v13
	v_and_or_b32 v13, v18, s37, v15
	v_ashrrev_i32_e32 v7, 31, v6
	v_lshlrev_b64 v[2:3], 11, v[2:3]
	v_lshlrev_b32_e32 v145, 7, v13
	v_ashrrev_i32_e32 v13, 31, v12
	v_lshlrev_b64 v[6:7], 11, v[6:7]
	v_lshl_add_u64 v[2:3], v[2:3], 0, s[22:23]
	v_lshlrev_b64 v[12:13], 11, v[12:13]
	v_readlane_b32 s30, v223, 0
	v_lshl_add_u64 v[6:7], v[6:7], 0, s[22:23]
	v_lshl_add_u64 v[2:3], v[2:3], 0, v[164:165]
	v_or_b32_e32 v12, v12, v164
	v_readlane_b32 s31, v223, 1
	v_lshl_add_u64 v[6:7], v[6:7], 0, v[164:165]
	v_lshl_add_u64 v[138:139], s[6:7], 0, v[2:3]
	v_mov_b32_e32 v2, 0
	v_lshlrev_b32_e32 v143, 4, v19
	v_lshl_add_u64 v[130:131], s[30:31], 0, v[12:13]
	v_lshl_add_u64 v[132:133], s[6:7], 0, v[6:7]
	s_mov_b32 s25, 0
	s_mov_b64 s[22:23], 0
	s_mov_b32 s27, 0x10000
	v_mov_b32_e32 v3, v2
	v_mov_b32_e32 v4, v2
	v_mov_b32_e32 v5, v2
	v_mov_b32_e32 v6, v2
	v_mov_b32_e32 v7, v2
	v_mov_b32_e32 v8, v2
	v_mov_b32_e32 v9, v2
	v_mov_b32_e32 v10, v2
	v_mov_b32_e32 v11, v2
	v_mov_b32_e32 v12, v2
	v_mov_b32_e32 v13, v2
	v_mov_b32_e32 v14, v2
	v_mov_b32_e32 v15, v2
	v_mov_b32_e32 v16, v2
	v_mov_b32_e32 v17, v2
	v_mov_b32_e32 v18, v2
	v_mov_b32_e32 v19, v2
	v_mov_b32_e32 v20, v2
	v_mov_b32_e32 v21, v2
	v_mov_b32_e32 v22, v2
	v_mov_b32_e32 v23, v2
	v_mov_b32_e32 v24, v2
	v_mov_b32_e32 v25, v2
	v_mov_b32_e32 v26, v2
	v_mov_b32_e32 v27, v2
	v_mov_b32_e32 v28, v2
	v_mov_b32_e32 v29, v2
	v_mov_b32_e32 v30, v2
	v_mov_b32_e32 v31, v2
	v_mov_b32_e32 v32, v2
	v_mov_b32_e32 v33, v2
	v_mov_b32_e32 v34, v2
	v_mov_b32_e32 v35, v2
	v_mov_b32_e32 v36, v2
	v_mov_b32_e32 v37, v2
	v_mov_b32_e32 v38, v2
	v_mov_b32_e32 v39, v2
	v_mov_b32_e32 v40, v2
	v_mov_b32_e32 v41, v2
	v_mov_b32_e32 v42, v2
	v_mov_b32_e32 v43, v2
	v_mov_b32_e32 v44, v2
	v_mov_b32_e32 v45, v2
	v_mov_b32_e32 v46, v2
	v_mov_b32_e32 v47, v2
	v_mov_b32_e32 v48, v2
	v_mov_b32_e32 v49, v2
	v_mov_b32_e32 v50, v2
	v_mov_b32_e32 v51, v2
	v_mov_b32_e32 v52, v2
	v_mov_b32_e32 v53, v2
	v_mov_b32_e32 v54, v2
	v_mov_b32_e32 v55, v2
	v_mov_b32_e32 v56, v2
	v_mov_b32_e32 v57, v2
	v_mov_b32_e32 v58, v2
	v_mov_b32_e32 v59, v2
	v_mov_b32_e32 v60, v2
	v_mov_b32_e32 v61, v2
	v_mov_b32_e32 v62, v2
	v_mov_b32_e32 v63, v2
	v_mov_b32_e32 v64, v2
	v_mov_b32_e32 v65, v2
	v_mov_b32_e32 v66, v2
	v_mov_b32_e32 v67, v2
	v_mov_b32_e32 v68, v2
	v_mov_b32_e32 v69, v2
	v_mov_b32_e32 v70, v2
	v_mov_b32_e32 v71, v2
	v_mov_b32_e32 v72, v2
	v_mov_b32_e32 v73, v2
	v_mov_b32_e32 v74, v2
	v_mov_b32_e32 v75, v2
	v_mov_b32_e32 v76, v2
	v_mov_b32_e32 v77, v2
	v_mov_b32_e32 v78, v2
	v_mov_b32_e32 v79, v2
	v_mov_b32_e32 v80, v2
	v_mov_b32_e32 v81, v2
	v_mov_b32_e32 v82, v2
	v_mov_b32_e32 v83, v2
	v_mov_b32_e32 v84, v2
	v_mov_b32_e32 v85, v2
	v_mov_b32_e32 v86, v2
	v_mov_b32_e32 v87, v2
	v_mov_b32_e32 v88, v2
	v_mov_b32_e32 v89, v2
	v_mov_b32_e32 v90, v2
	v_mov_b32_e32 v91, v2
	v_mov_b32_e32 v92, v2
	v_mov_b32_e32 v93, v2
	v_mov_b32_e32 v94, v2
	v_mov_b32_e32 v95, v2
	v_mov_b32_e32 v96, v2
	v_mov_b32_e32 v97, v2
	v_mov_b32_e32 v98, v2
	v_mov_b32_e32 v99, v2
	v_mov_b32_e32 v100, v2
	v_mov_b32_e32 v101, v2
	v_mov_b32_e32 v102, v2
	v_mov_b32_e32 v103, v2
	v_mov_b32_e32 v104, v2
	v_mov_b32_e32 v105, v2
	v_mov_b32_e32 v106, v2
	v_mov_b32_e32 v107, v2
	v_mov_b32_e32 v108, v2
	v_mov_b32_e32 v109, v2
	v_mov_b32_e32 v110, v2
	v_mov_b32_e32 v111, v2
	v_mov_b32_e32 v112, v2
	v_mov_b32_e32 v113, v2
	v_mov_b32_e32 v114, v2
	v_mov_b32_e32 v115, v2
	v_mov_b32_e32 v116, v2
	v_mov_b32_e32 v117, v2
	v_mov_b32_e32 v118, v2
	v_mov_b32_e32 v119, v2
	v_mov_b32_e32 v120, v2
	v_mov_b32_e32 v121, v2
	v_mov_b32_e32 v122, v2
	v_mov_b32_e32 v123, v2
	v_mov_b32_e32 v124, v2
	v_mov_b32_e32 v125, v2
	v_mov_b32_e32 v126, v2
	v_mov_b32_e32 v127, v2
	v_mov_b32_e32 v128, v2
	v_mov_b32_e32 v129, v2
	s_waitcnt lgkmcnt(0)
	s_barrier
	v_mov_b32_e32 v147, v145
	v_mov_b32_e32 v148, v146
	s_add_u32 s22, s22, 0x80
	s_addc_u32 s23, s23, 0
	s_add_i32 s27, s27, 0x10000
	v_add_u32_e32 v252, v147, v141
	v_add_u32_e32 v253, v148, v141
	ds_read_b128 v[224:227], v252
	ds_read_b128 v[232:235], v253 offset:32768
	ds_read_b128 v[228:231], v252 offset:4096
	ds_read_b128 v[236:239], v253 offset:36864
	ds_read_b128 v[240:243], v253 offset:40960
	ds_read_b128 v[244:247], v253 offset:45056
; #define MFMA(a, b, c) __builtin_amdgcn_mfma_f32_32x32x16_bf16((a), (b), (c), 0, 0, 0)
; #define GEMM_ISSUE(KT, ST) do { const int k1_ = (KT) << 6; unsigned char* d_ = ldst + (ST) * STAGE; \
;         _Pragma("unroll") for (int j_ = 0; j_ < 4; ++j_) dma16(ap + (size_t)(64 * j_) * lda + k1_, d_ + j_ * 8192); \
;         _Pragma("unroll") for (int j_ = 0; j_ < NBW; ++j_) dma16(bp + bro[j_] + k1_, d_ + BOFF + j_ * 8192); } while (0)
; template <int NBW>
; DI void gemm_mainloop(f32x16 (&acc)[2][NBW], const bf16_t* A, size_t lda, int m0, const bf16_t* Bt, size_t ldb, int n0, int K, unsigned char* lds, bool pre = false, bool only_issue = false) {
;     ...
;     for (int kt = 0; kt < nk; ++kt) {
;         const unsigned char* st = lds + (kt & 1) * STAGE;
; #pragma unroll
;         for (int s = 0; s < 4; ++s) {
;             if (s == 1 && kt + 1 < nk) GEMM_ISSUE(kt + 1, (kt + 1) & 1);
;             bf16x8 a[2], b[NBW];
; #pragma unroll
;             for (int mb = 0; mb < 2; ++mb) a[mb] = *(const bf16x8*)(st + aofs + mb * 4096 + xo[s]);
; #pragma unroll
;             for (int nb = 0; nb < NBW; ++nb) b[nb] = *(const bf16x8*)(st + bofs + nb * 4096 + xo[s]);
; #pragma unroll
;             for (int mb = 0; mb < 2; ++mb)
; #pragma unroll
;                 for (int nb = 0; nb < NBW; ++nb) acc[mb][nb] = MFMA(a[mb], b[nb], acc[mb][nb]);
;         }
;         __syncthreads();
;     }
.Lp5_kloop:
	s_waitcnt lgkmcnt(4)
	v_mfma_f32_32x32x16_bf16 v[114:129], v[224:227], v[232:235], v[114:129]
	v_add_u32_e32 v252, v147, v142
	v_add_u32_e32 v253, v148, v142
	ds_read_b128 v[150:153], v252
	s_waitcnt lgkmcnt(4)
	v_mfma_f32_32x32x16_bf16 v[50:65], v[228:231], v[232:235], v[50:65]
	ds_read_b128 v[158:161], v253 offset:32768
	s_waitcnt lgkmcnt(4)
	v_mfma_f32_32x32x16_bf16 v[98:113], v[224:227], v[236:239], v[98:113]
	ds_read_b128 v[154:157], v252 offset:4096
	v_mfma_f32_32x32x16_bf16 v[34:49], v[228:231], v[236:239], v[34:49]
	ds_read_b128 v[170:173], v253 offset:36864
	s_waitcnt lgkmcnt(5)
	v_mfma_f32_32x32x16_bf16 v[82:97], v[224:227], v[240:243], v[82:97]
	ds_read_b128 v[174:177], v253 offset:40960
	v_mfma_f32_32x32x16_bf16 v[18:33], v[228:231], v[240:243], v[18:33]
	ds_read_b128 v[178:181], v253 offset:45056
	s_waitcnt lgkmcnt(6)
	v_mfma_f32_32x32x16_bf16 v[66:81], v[224:227], v[244:247], v[66:81]
	v_mfma_f32_32x32x16_bf16 v[2:17], v[228:231], v[244:247], v[2:17]
	s_waitcnt lgkmcnt(4)
	v_mfma_f32_32x32x16_bf16 v[114:129], v[150:153], v[158:161], v[114:129]
	v_add_u32_e32 v252, v147, v143
	v_add_u32_e32 v253, v148, v143
	ds_read_b128 v[224:227], v252
	s_waitcnt lgkmcnt(4)
	v_mfma_f32_32x32x16_bf16 v[50:65], v[154:157], v[158:161], v[50:65]
	ds_read_b128 v[232:235], v253 offset:32768
	s_waitcnt lgkmcnt(4)
	v_mfma_f32_32x32x16_bf16 v[98:113], v[150:153], v[170:173], v[98:113]
	ds_read_b128 v[228:231], v252 offset:4096
	v_mfma_f32_32x32x16_bf16 v[34:49], v[154:157], v[170:173], v[34:49]
	ds_read_b128 v[236:239], v253 offset:36864
	s_waitcnt lgkmcnt(5)
	v_mfma_f32_32x32x16_bf16 v[82:97], v[150:153], v[174:177], v[82:97]
	ds_read_b128 v[240:243], v253 offset:40960
	v_mfma_f32_32x32x16_bf16 v[18:33], v[154:157], v[174:177], v[18:33]
	ds_read_b128 v[244:247], v253 offset:45056
	s_waitcnt lgkmcnt(6)
	v_mfma_f32_32x32x16_bf16 v[66:81], v[150:153], v[178:181], v[66:81]
	v_mfma_f32_32x32x16_bf16 v[2:17], v[154:157], v[178:181], v[2:17]
	s_waitcnt lgkmcnt(4)
	v_mfma_f32_32x32x16_bf16 v[114:129], v[224:227], v[232:235], v[114:129]
	v_add_u32_e32 v252, v147, v144
	v_add_u32_e32 v253, v148, v144
	ds_read_b128 v[150:153], v252
	s_waitcnt lgkmcnt(4)
	v_mfma_f32_32x32x16_bf16 v[50:65], v[228:231], v[232:235], v[50:65]
	ds_read_b128 v[158:161], v253 offset:32768
	s_waitcnt lgkmcnt(4)
	v_mfma_f32_32x32x16_bf16 v[98:113], v[224:227], v[236:239], v[98:113]
	ds_read_b128 v[154:157], v252 offset:4096
	v_mfma_f32_32x32x16_bf16 v[34:49], v[228:231], v[236:239], v[34:49]
	ds_read_b128 v[170:173], v253 offset:36864
	s_waitcnt lgkmcnt(5)
	v_mfma_f32_32x32x16_bf16 v[82:97], v[224:227], v[240:243], v[82:97]
	ds_read_b128 v[174:177], v253 offset:40960
	v_mfma_f32_32x32x16_bf16 v[18:33], v[228:231], v[240:243], v[18:33]
	ds_read_b128 v[178:181], v253 offset:45056
	s_waitcnt lgkmcnt(6)
	v_mfma_f32_32x32x16_bf16 v[66:81], v[224:227], v[244:247], v[66:81]
	v_mfma_f32_32x32x16_bf16 v[2:17], v[228:231], v[244:247], v[2:17]
	v_xor_b32_e32 v147, 0x10000, v147
	v_xor_b32_e32 v148, 0x10000, v148
	s_waitcnt vmcnt(0) lgkmcnt(0)
	s_barrier
	s_cmp_eq_u32 s22, 0x800
	s_cbranch_scc1 .Lp5_klast
	s_cmp_eq_u32 s22, 0x780
	s_cbranch_scc1 .Lp5_knodma
	v_mfma_f32_32x32x16_bf16 v[114:129], v[150:153], v[158:161], v[114:129]
	v_add_u32_e32 v252, v147, v141
	v_add_u32_e32 v253, v148, v141
	ds_read_b128 v[224:227], v252
	s_and_b32 s29, s27, 0x10000
	v_add_u32_e32 v250, s29, v140
	v_lshl_add_u64 v[248:249], v[130:131], 0, s[22:23]
	s_nop 0
	v_readfirstlane_b32 s29, v250
	v_lshl_add_u64 v[250:251], v[248:249], 0, s[14:15]
	s_mov_b32 m0, s29
	s_nop 0
	global_load_lds_dwordx4 v[250:251], off
	v_mfma_f32_32x32x16_bf16 v[50:65], v[154:157], v[158:161], v[50:65]
	ds_read_b128 v[232:235], v253 offset:32768
	v_lshl_add_u64 v[250:251], v[248:249], 0, s[16:17]
	s_add_i32 m0, s29, 0x2000
	s_nop 0
	global_load_lds_dwordx4 v[250:251], off
	v_mfma_f32_32x32x16_bf16 v[98:113], v[150:153], v[170:173], v[98:113]
	ds_read_b128 v[228:231], v252 offset:4096
	v_lshl_add_u64 v[250:251], v[248:249], 0, s[18:19]
	s_add_i32 m0, s29, 0x4000
	s_nop 0
	global_load_lds_dwordx4 v[250:251], off
	v_mfma_f32_32x32x16_bf16 v[34:49], v[154:157], v[170:173], v[34:49]
	ds_read_b128 v[236:239], v253 offset:36864
	v_lshl_add_u64 v[250:251], v[248:249], 0, s[20:21]
	s_add_i32 m0, s29, 0x6000
	s_nop 0
	global_load_lds_dwordx4 v[250:251], off
	v_mfma_f32_32x32x16_bf16 v[82:97], v[150:153], v[174:177], v[82:97]
	ds_read_b128 v[240:243], v253 offset:40960
	v_lshl_add_u64 v[250:251], v[132:133], 0, s[22:23]
	s_add_i32 m0, s29, 0x8000
	s_nop 0
	global_load_lds_dwordx4 v[250:251], off
	v_mfma_f32_32x32x16_bf16 v[18:33], v[154:157], v[174:177], v[18:33]
	ds_read_b128 v[244:247], v253 offset:45056
	v_lshl_add_u64 v[250:251], v[134:135], 0, s[22:23]
	s_add_i32 m0, s29, 0xa000
	s_nop 0
	global_load_lds_dwordx4 v[250:251], off
	v_mfma_f32_32x32x16_bf16 v[66:81], v[150:153], v[178:181], v[66:81]
	v_lshl_add_u64 v[250:251], v[136:137], 0, s[22:23]
	s_add_i32 m0, s29, 0xc000
	s_nop 0
	global_load_lds_dwordx4 v[250:251], off
	v_mfma_f32_32x32x16_bf16 v[2:17], v[154:157], v[178:181], v[2:17]
	v_lshl_add_u64 v[250:251], v[138:139], 0, s[22:23]
	s_add_i32 m0, s29, 0xe000
	s_nop 0
	global_load_lds_dwordx4 v[250:251], off
	s_add_u32 s22, s22, 0x80
	s_addc_u32 s23, s23, 0
	s_add_i32 s27, s27, 0x10000
	s_branch .Lp5_kloop
.Lp5_knodma:
	v_mfma_f32_32x32x16_bf16 v[114:129], v[150:153], v[158:161], v[114:129]
	v_add_u32_e32 v252, v147, v141
	v_add_u32_e32 v253, v148, v141
	ds_read_b128 v[224:227], v252
	v_mfma_f32_32x32x16_bf16 v[50:65], v[154:157], v[158:161], v[50:65]
	ds_read_b128 v[232:235], v253 offset:32768
	v_mfma_f32_32x32x16_bf16 v[98:113], v[150:153], v[170:173], v[98:113]
	ds_read_b128 v[228:231], v252 offset:4096
	v_mfma_f32_32x32x16_bf16 v[34:49], v[154:157], v[170:173], v[34:49]
	ds_read_b128 v[236:239], v253 offset:36864
	v_mfma_f32_32x32x16_bf16 v[82:97], v[150:153], v[174:177], v[82:97]
	ds_read_b128 v[240:243], v253 offset:40960
	v_mfma_f32_32x32x16_bf16 v[18:33], v[154:157], v[174:177], v[18:33]
	ds_read_b128 v[244:247], v253 offset:45056
	v_mfma_f32_32x32x16_bf16 v[66:81], v[150:153], v[178:181], v[66:81]
	v_mfma_f32_32x32x16_bf16 v[2:17], v[154:157], v[178:181], v[2:17]
	s_add_u32 s22, s22, 0x80
	s_addc_u32 s23, s23, 0
	s_add_i32 s27, s27, 0x10000
	s_branch .Lp5_kloop
.Lp5_klast:
	v_mfma_f32_32x32x16_bf16 v[114:129], v[150:153], v[158:161], v[114:129]
	v_mfma_f32_32x32x16_bf16 v[50:65], v[154:157], v[158:161], v[50:65]
	v_mfma_f32_32x32x16_bf16 v[98:113], v[150:153], v[170:173], v[98:113]
	v_mfma_f32_32x32x16_bf16 v[34:49], v[154:157], v[170:173], v[34:49]
	v_mfma_f32_32x32x16_bf16 v[82:97], v[150:153], v[174:177], v[82:97]
	v_mfma_f32_32x32x16_bf16 v[18:33], v[154:157], v[174:177], v[18:33]
	v_mfma_f32_32x32x16_bf16 v[66:81], v[150:153], v[178:181], v[66:81]
	v_mfma_f32_32x32x16_bf16 v[2:17], v[154:157], v[178:181], v[2:17]
	s_mov_b32 s25, 16
	s_mov_b32 s29, 0x10000

; DI int opaque_tid() { int t = threadIdx.x; asm volatile("" : "+v"(t)); return t; }
; #define GEMM_ISSUE(KT, ST) do { const int k1_ = (KT) << 6; unsigned char* d_ = ldst + (ST) * STAGE; \
;         _Pragma("unroll") for (int j_ = 0; j_ < 4; ++j_) dma16(ap + (size_t)(64 * j_) * lda + k1_, d_ + j_ * 8192); \
;         _Pragma("unroll") for (int j_ = 0; j_ < NBW; ++j_) dma16(bp + bro[j_] + k1_, d_ + BOFF + j_ * 8192); } while (0)
; template <int NBW>
; DI void gemm_mainloop(f32x16 (&acc)[2][NBW], const bf16_t* A, size_t lda, int m0, const bf16_t* Bt, size_t ldb, int n0, int K, unsigned char* lds, bool pre = false, bool only_issue = false) {
;     ...
;     const int t = opaque_tid(), w = t >> 6, lane = t & 63, r = lane & 31, hh = lane >> 5, wm = w >> 1, wn = w & 1;
;     const int drow = w * 8 + (lane >> 3);
;     const int lchunk = (lane & 7) ^ ((drow >> 1) & 7);
;     const bf16_t* ap = A + (size_t)(m0 + drow) * lda + lchunk * 8;
;     const bf16_t* bp = Bt + (size_t)n0 * ldb + lchunk * 8;
;     size_t bro[NBW];
; #pragma unroll
;     for (int j = 0; j < NBW; ++j) {
;         const int rho = 64 * j + drow; const int wnh = rho / (32 * NBW), wi = rho % (32 * NBW);
;         bro[j] = (size_t)(wnh * 32 * NBW + NBW * (wi & 31) + (wi >> 5)) * ldb;
;     }
;     unsigned char* ldst = lds + w * 1024 + lane * 16;
;     ...
;     if (!pre) GEMM_ISSUE(0, 0);
;     if (only_issue) return;
;     __syncthreads();
;     const int nk = K >> 6;
;     const int xr = (r >> 1) & 7;
;     int xo[4];
; #pragma unroll
;     for (int s = 0; s < 4; ++s) xo[s] = ((2 * s + hh) ^ xr) << 4;
;     const int aofs = (wm * 64 + r) * 128;
;     const int bofs = BOFF + (wn * 32 * NBW + r) * 128;
.LBB0_1638:
	v_lshrrev_b32_e32 v16, 5, v14
	v_lshrrev_b32_e32 v17, 3, v14
	v_lshrrev_b32_e32 v14, 1, v13
	v_and_b32_e32 v15, 31, v13
	v_lshrrev_b32_e32 v18, 6, v13
	v_bfe_u32 v13, v13, 1, 3
	v_bitop3_b32 v19, v16, v14, 7 bitop3:0x78
	v_lshlrev_b32_e32 v7, 7, v7
	v_lshlrev_b32_e32 v165, 4, v19
	v_bitop3_b32 v19, v16, v13, 2 bitop3:0x36
	v_and_or_b32 v7, v7, s36, v15
	v_lshlrev_b32_e32 v166, 4, v19
	v_bitop3_b32 v19, v16, v13, 4 bitop3:0x36
	v_bitop3_b32 v13, v16, v13, 6 bitop3:0x36
	v_lshlrev_b32_e32 v170, 7, v7
	v_add_u32_e32 v7, s41, v8
	v_lshlrev_b32_e32 v168, 4, v13
	v_and_or_b32 v13, v14, s38, v15
	v_add3_u32 v14, v7, v2, s36
	v_lshlrev_b16_e32 v2, 3, v18
	v_or_b32_e32 v7, v2, v17
	v_sub_u16_e32 v2, v7, v3
	v_and_b32_e32 v2, 31, v2
	v_lshl_add_u32 v2, v2, 2, v9
	v_ashrrev_i32_e32 v3, 31, v2
	v_lshlrev_b64 v[2:3], 11, v[2:3]
	v_lshl_add_u64 v[2:3], v[2:3], 0, s[28:29]
	v_lshl_add_u64 v[2:3], v[2:3], 0, v[132:133]
	v_lshl_add_u64 v[136:137], s[8:9], 0, v[2:3]
	v_sub_u16_e32 v2, v7, v4
	v_and_b32_e32 v2, 31, v2
	v_lshl_add_u32 v2, v2, 2, v10
	v_ashrrev_i32_e32 v3, 31, v2
	v_lshlrev_b64 v[2:3], 11, v[2:3]
	v_lshl_add_u64 v[2:3], v[2:3], 0, s[28:29]
	v_lshl_add_u64 v[2:3], v[2:3], 0, v[132:133]
	v_lshl_add_u64 v[138:139], s[8:9], 0, v[2:3]
	v_sub_u16_e32 v2, v7, v5
	v_and_b32_e32 v2, 31, v2
	v_lshl_add_u32 v2, v2, 2, v11
	v_ashrrev_i32_e32 v3, 31, v2
	v_lshlrev_b64 v[2:3], 11, v[2:3]
	v_lshl_add_u64 v[2:3], v[2:3], 0, s[28:29]
	v_lshl_add_u64 v[2:3], v[2:3], 0, v[132:133]
	v_lshl_add_u64 v[140:141], s[8:9], 0, v[2:3]
	v_sub_u16_e32 v2, v7, v6
	v_and_b32_e32 v2, 31, v2
	v_lshl_add_u32 v2, v2, 2, v12
	v_ashrrev_i32_e32 v3, 31, v2
	v_lshlrev_b64 v[2:3], 11, v[2:3]
	v_ashrrev_i32_e32 v15, 31, v14
	v_lshl_add_u64 v[2:3], v[2:3], 0, s[28:29]
	v_lshlrev_b64 v[14:15], 11, v[14:15]
	v_lshl_add_u64 v[2:3], v[2:3], 0, v[132:133]
	v_or_b32_e32 v14, v14, v132
	v_lshl_add_u64 v[142:143], s[8:9], 0, v[2:3]
	v_mov_b32_e32 v2, 0
	v_lshlrev_b32_e32 v167, 4, v19
	v_lshlrev_b32_e32 v169, 7, v13
	v_lshl_add_u64 v[134:135], s[50:51], 0, v[14:15]
	s_mov_b32 s25, 0
	s_mov_b64 s[28:29], 0
	s_mov_b32 s27, 0x10000
	v_mov_b32_e32 v3, v2
	v_mov_b32_e32 v4, v2
	v_mov_b32_e32 v5, v2
	v_mov_b32_e32 v6, v2
	v_mov_b32_e32 v7, v2
	v_mov_b32_e32 v8, v2
	v_mov_b32_e32 v9, v2
	v_mov_b32_e32 v10, v2
	v_mov_b32_e32 v11, v2
	v_mov_b32_e32 v12, v2
	v_mov_b32_e32 v13, v2
	v_mov_b32_e32 v14, v2
	v_mov_b32_e32 v15, v2
	v_mov_b32_e32 v16, v2
	v_mov_b32_e32 v17, v2
	v_mov_b32_e32 v18, v2
	v_mov_b32_e32 v19, v2
	v_mov_b32_e32 v20, v2
	v_mov_b32_e32 v21, v2
	v_mov_b32_e32 v22, v2
	v_mov_b32_e32 v23, v2
	v_mov_b32_e32 v24, v2
	v_mov_b32_e32 v25, v2
	v_mov_b32_e32 v26, v2
	v_mov_b32_e32 v27, v2
	v_mov_b32_e32 v28, v2
	v_mov_b32_e32 v29, v2
	v_mov_b32_e32 v30, v2
	v_mov_b32_e32 v31, v2
	v_mov_b32_e32 v32, v2
	v_mov_b32_e32 v33, v2
	v_mov_b32_e32 v34, v2
	v_mov_b32_e32 v35, v2
	v_mov_b32_e32 v36, v2
	v_mov_b32_e32 v37, v2
	v_mov_b32_e32 v38, v2
	v_mov_b32_e32 v39, v2
	v_mov_b32_e32 v40, v2
	v_mov_b32_e32 v41, v2
	v_mov_b32_e32 v42, v2
	v_mov_b32_e32 v43, v2
	v_mov_b32_e32 v44, v2
	v_mov_b32_e32 v45, v2
	v_mov_b32_e32 v46, v2
	v_mov_b32_e32 v47, v2
	v_mov_b32_e32 v48, v2
	v_mov_b32_e32 v49, v2
	v_mov_b32_e32 v50, v2
	v_mov_b32_e32 v51, v2
	v_mov_b32_e32 v52, v2
	v_mov_b32_e32 v53, v2
	v_mov_b32_e32 v54, v2
	v_mov_b32_e32 v55, v2
	v_mov_b32_e32 v56, v2
	v_mov_b32_e32 v57, v2
	v_mov_b32_e32 v58, v2
	v_mov_b32_e32 v59, v2
	v_mov_b32_e32 v60, v2
	v_mov_b32_e32 v61, v2
	v_mov_b32_e32 v62, v2
	v_mov_b32_e32 v63, v2
	v_mov_b32_e32 v64, v2
	v_mov_b32_e32 v65, v2
	v_mov_b32_e32 v66, v2
	v_mov_b32_e32 v67, v2
	v_mov_b32_e32 v68, v2
	v_mov_b32_e32 v69, v2
	v_mov_b32_e32 v70, v2
	v_mov_b32_e32 v71, v2
	v_mov_b32_e32 v72, v2
	v_mov_b32_e32 v73, v2
	v_mov_b32_e32 v74, v2
	v_mov_b32_e32 v75, v2
	v_mov_b32_e32 v76, v2
	v_mov_b32_e32 v77, v2
	v_mov_b32_e32 v78, v2
	v_mov_b32_e32 v79, v2
	v_mov_b32_e32 v80, v2
	v_mov_b32_e32 v81, v2
	v_mov_b32_e32 v82, v2
	v_mov_b32_e32 v83, v2
	v_mov_b32_e32 v84, v2
	v_mov_b32_e32 v85, v2
	v_mov_b32_e32 v86, v2
	v_mov_b32_e32 v87, v2
	v_mov_b32_e32 v88, v2
	v_mov_b32_e32 v89, v2
	v_mov_b32_e32 v90, v2
	v_mov_b32_e32 v91, v2
	v_mov_b32_e32 v92, v2
	v_mov_b32_e32 v93, v2
	v_mov_b32_e32 v94, v2
	v_mov_b32_e32 v95, v2
	v_mov_b32_e32 v96, v2
	v_mov_b32_e32 v97, v2
	v_mov_b32_e32 v98, v2
	v_mov_b32_e32 v99, v2
	v_mov_b32_e32 v100, v2
	v_mov_b32_e32 v101, v2
	v_mov_b32_e32 v102, v2
	v_mov_b32_e32 v103, v2
	v_mov_b32_e32 v104, v2
	v_mov_b32_e32 v105, v2
	v_mov_b32_e32 v106, v2
	v_mov_b32_e32 v107, v2
	v_mov_b32_e32 v108, v2
	v_mov_b32_e32 v109, v2
	v_mov_b32_e32 v110, v2
	v_mov_b32_e32 v111, v2
	v_mov_b32_e32 v112, v2
	v_mov_b32_e32 v113, v2
	v_mov_b32_e32 v114, v2
	v_mov_b32_e32 v115, v2
	v_mov_b32_e32 v116, v2
	v_mov_b32_e32 v117, v2
	v_mov_b32_e32 v118, v2
	v_mov_b32_e32 v119, v2
	v_mov_b32_e32 v120, v2
	v_mov_b32_e32 v121, v2
	v_mov_b32_e32 v122, v2
	v_mov_b32_e32 v123, v2
	v_mov_b32_e32 v124, v2
	v_mov_b32_e32 v125, v2
	v_mov_b32_e32 v126, v2
	v_mov_b32_e32 v127, v2
	v_mov_b32_e32 v128, v2
	v_mov_b32_e32 v129, v2
	s_waitcnt vmcnt(0) lgkmcnt(0)
	s_barrier
	v_mov_b32_e32 v132, v169
	v_mov_b32_e32 v171, v170
	s_add_u32 s28, s28, 0x80
	s_addc_u32 s29, s29, 0
	s_add_i32 s27, s27, 0x10000
	v_add_u32_e32 v252, v132, v165
	v_add_u32_e32 v253, v171, v165
	ds_read_b128 v[224:227], v252
	ds_read_b128 v[232:235], v253 offset:32768
	ds_read_b128 v[228:231], v252 offset:4096
	ds_read_b128 v[236:239], v253 offset:36864
	ds_read_b128 v[240:243], v253 offset:40960
	ds_read_b128 v[244:247], v253 offset:45056
; #define MFMA(a, b, c) __builtin_amdgcn_mfma_f32_32x32x16_bf16((a), (b), (c), 0, 0, 0)
; #define GEMM_ISSUE(KT, ST) do { const int k1_ = (KT) << 6; unsigned char* d_ = ldst + (ST) * STAGE; \
;         _Pragma("unroll") for (int j_ = 0; j_ < 4; ++j_) dma16(ap + (size_t)(64 * j_) * lda + k1_, d_ + j_ * 8192); \
;         _Pragma("unroll") for (int j_ = 0; j_ < NBW; ++j_) dma16(bp + bro[j_] + k1_, d_ + BOFF + j_ * 8192); } while (0)
; template <int NBW>
; DI void gemm_mainloop(f32x16 (&acc)[2][NBW], const bf16_t* A, size_t lda, int m0, const bf16_t* Bt, size_t ldb, int n0, int K, unsigned char* lds, bool pre = false, bool only_issue = false) {
;     ...
;     for (int kt = 0; kt < nk; ++kt) {
;         const unsigned char* st = lds + (kt & 1) * STAGE;
; #pragma unroll
;         for (int s = 0; s < 4; ++s) {
;             if (s == 1 && kt + 1 < nk) GEMM_ISSUE(kt + 1, (kt + 1) & 1);
;             bf16x8 a[2], b[NBW];
; #pragma unroll
;             for (int mb = 0; mb < 2; ++mb) a[mb] = *(const bf16x8*)(st + aofs + mb * 4096 + xo[s]);
; #pragma unroll
;             for (int nb = 0; nb < NBW; ++nb) b[nb] = *(const bf16x8*)(st + bofs + nb * 4096 + xo[s]);
; #pragma unroll
;             for (int mb = 0; mb < 2; ++mb)
; #pragma unroll
;                 for (int nb = 0; nb < NBW; ++nb) acc[mb][nb] = MFMA(a[mb], b[nb], acc[mb][nb]);
;         }
;         __syncthreads();
;     }
.Lp6_kloop:
	s_waitcnt lgkmcnt(4)
	v_mfma_f32_32x32x16_bf16 v[114:129], v[224:227], v[232:235], v[114:129]
	v_add_u32_e32 v252, v132, v166
	v_add_u32_e32 v253, v171, v166
	ds_read_b128 v[172:175], v252
	s_waitcnt lgkmcnt(4)
	v_mfma_f32_32x32x16_bf16 v[50:65], v[228:231], v[232:235], v[50:65]
	ds_read_b128 v[180:183], v253 offset:32768
	s_waitcnt lgkmcnt(4)
	v_mfma_f32_32x32x16_bf16 v[98:113], v[224:227], v[236:239], v[98:113]
	ds_read_b128 v[176:179], v252 offset:4096
	v_mfma_f32_32x32x16_bf16 v[34:49], v[228:231], v[236:239], v[34:49]
	ds_read_b128 v[184:187], v253 offset:36864
	s_waitcnt lgkmcnt(5)
	v_mfma_f32_32x32x16_bf16 v[82:97], v[224:227], v[240:243], v[82:97]
	ds_read_b128 v[188:191], v253 offset:40960
	v_mfma_f32_32x32x16_bf16 v[18:33], v[228:231], v[240:243], v[18:33]
	ds_read_b128 v[192:195], v253 offset:45056
	s_waitcnt lgkmcnt(6)
	v_mfma_f32_32x32x16_bf16 v[66:81], v[224:227], v[244:247], v[66:81]
	v_mfma_f32_32x32x16_bf16 v[2:17], v[228:231], v[244:247], v[2:17]
	s_waitcnt lgkmcnt(4)
	v_mfma_f32_32x32x16_bf16 v[114:129], v[172:175], v[180:183], v[114:129]
	v_add_u32_e32 v252, v132, v167
	v_add_u32_e32 v253, v171, v167
	ds_read_b128 v[224:227], v252
	s_waitcnt lgkmcnt(4)
	v_mfma_f32_32x32x16_bf16 v[50:65], v[176:179], v[180:183], v[50:65]
	ds_read_b128 v[232:235], v253 offset:32768
	s_waitcnt lgkmcnt(4)
	v_mfma_f32_32x32x16_bf16 v[98:113], v[172:175], v[184:187], v[98:113]
	ds_read_b128 v[228:231], v252 offset:4096
	v_mfma_f32_32x32x16_bf16 v[34:49], v[176:179], v[184:187], v[34:49]
	ds_read_b128 v[236:239], v253 offset:36864
	s_waitcnt lgkmcnt(5)
	v_mfma_f32_32x32x16_bf16 v[82:97], v[172:175], v[188:191], v[82:97]
	ds_read_b128 v[240:243], v253 offset:40960
	v_mfma_f32_32x32x16_bf16 v[18:33], v[176:179], v[188:191], v[18:33]
	ds_read_b128 v[244:247], v253 offset:45056
	s_waitcnt lgkmcnt(6)
	v_mfma_f32_32x32x16_bf16 v[66:81], v[172:175], v[192:195], v[66:81]
	v_mfma_f32_32x32x16_bf16 v[2:17], v[176:179], v[192:195], v[2:17]
	s_waitcnt lgkmcnt(4)
	v_mfma_f32_32x32x16_bf16 v[114:129], v[224:227], v[232:235], v[114:129]
	v_add_u32_e32 v252, v132, v168
	v_add_u32_e32 v253, v171, v168
	ds_read_b128 v[172:175], v252
	s_waitcnt lgkmcnt(4)
	v_mfma_f32_32x32x16_bf16 v[50:65], v[228:231], v[232:235], v[50:65]
	ds_read_b128 v[180:183], v253 offset:32768
	s_waitcnt lgkmcnt(4)
	v_mfma_f32_32x32x16_bf16 v[98:113], v[224:227], v[236:239], v[98:113]
	ds_read_b128 v[176:179], v252 offset:4096
	v_mfma_f32_32x32x16_bf16 v[34:49], v[228:231], v[236:239], v[34:49]
	ds_read_b128 v[184:187], v253 offset:36864
	s_waitcnt lgkmcnt(5)
	v_mfma_f32_32x32x16_bf16 v[82:97], v[224:227], v[240:243], v[82:97]
	ds_read_b128 v[188:191], v253 offset:40960
	v_mfma_f32_32x32x16_bf16 v[18:33], v[228:231], v[240:243], v[18:33]
	ds_read_b128 v[192:195], v253 offset:45056
	s_waitcnt lgkmcnt(6)
	v_mfma_f32_32x32x16_bf16 v[66:81], v[224:227], v[244:247], v[66:81]
	v_mfma_f32_32x32x16_bf16 v[2:17], v[228:231], v[244:247], v[2:17]
	v_xor_b32_e32 v132, 0x10000, v132
	v_xor_b32_e32 v171, 0x10000, v171
	s_waitcnt vmcnt(0) lgkmcnt(0)
	s_barrier
	s_cmp_eq_u32 s28, 0x800
	s_cbranch_scc1 .Lp6_klast
	s_cmp_eq_u32 s28, 0x780
	s_cbranch_scc1 .Lp6_knodma
	v_mfma_f32_32x32x16_bf16 v[114:129], v[172:175], v[180:183], v[114:129]
	v_add_u32_e32 v252, v132, v165
	v_add_u32_e32 v253, v171, v165
	ds_read_b128 v[224:227], v252
	s_and_b32 s30, s27, 0x10000
	v_add_u32_e32 v250, s30, v164
	v_lshl_add_u64 v[248:249], v[134:135], 0, s[28:29]
	s_nop 0
	v_readfirstlane_b32 s30, v250
	v_lshl_add_u64 v[250:251], v[248:249], 0, s[16:17]
	s_mov_b32 m0, s30
	s_nop 0
	global_load_lds_dwordx4 v[250:251], off
	v_mfma_f32_32x32x16_bf16 v[50:65], v[176:179], v[180:183], v[50:65]
	ds_read_b128 v[232:235], v253 offset:32768
	v_lshl_add_u64 v[250:251], v[248:249], 0, s[18:19]
	s_add_i32 m0, s30, 0x2000
	s_nop 0
	global_load_lds_dwordx4 v[250:251], off
	v_mfma_f32_32x32x16_bf16 v[98:113], v[172:175], v[184:187], v[98:113]
	ds_read_b128 v[228:231], v252 offset:4096
	v_lshl_add_u64 v[250:251], v[248:249], 0, s[20:21]
	s_add_i32 m0, s30, 0x4000
	s_nop 0
	global_load_lds_dwordx4 v[250:251], off
	v_mfma_f32_32x32x16_bf16 v[34:49], v[176:179], v[184:187], v[34:49]
	ds_read_b128 v[236:239], v253 offset:36864
	v_lshl_add_u64 v[250:251], v[248:249], 0, s[22:23]
	s_add_i32 m0, s30, 0x6000
	s_nop 0
	global_load_lds_dwordx4 v[250:251], off
	v_mfma_f32_32x32x16_bf16 v[82:97], v[172:175], v[188:191], v[82:97]
	ds_read_b128 v[240:243], v253 offset:40960
	v_lshl_add_u64 v[250:251], v[136:137], 0, s[28:29]
	s_add_i32 m0, s30, 0x8000
	s_nop 0
	global_load_lds_dwordx4 v[250:251], off
	v_mfma_f32_32x32x16_bf16 v[18:33], v[176:179], v[188:191], v[18:33]
	ds_read_b128 v[244:247], v253 offset:45056
	v_lshl_add_u64 v[250:251], v[138:139], 0, s[28:29]
	s_add_i32 m0, s30, 0xa000
	s_nop 0
	global_load_lds_dwordx4 v[250:251], off
	v_mfma_f32_32x32x16_bf16 v[66:81], v[172:175], v[192:195], v[66:81]
	v_lshl_add_u64 v[250:251], v[140:141], 0, s[28:29]
	s_add_i32 m0, s30, 0xc000
	s_nop 0
	global_load_lds_dwordx4 v[250:251], off
	v_mfma_f32_32x32x16_bf16 v[2:17], v[176:179], v[192:195], v[2:17]
	v_lshl_add_u64 v[250:251], v[142:143], 0, s[28:29]
	s_add_i32 m0, s30, 0xe000
	s_nop 0
	global_load_lds_dwordx4 v[250:251], off
	s_add_u32 s28, s28, 0x80
	s_addc_u32 s29, s29, 0
	s_add_i32 s27, s27, 0x10000
	s_branch .Lp6_kloop
.Lp6_knodma:
	v_mfma_f32_32x32x16_bf16 v[114:129], v[172:175], v[180:183], v[114:129]
	v_add_u32_e32 v252, v132, v165
	v_add_u32_e32 v253, v171, v165
	ds_read_b128 v[224:227], v252
	v_mfma_f32_32x32x16_bf16 v[50:65], v[176:179], v[180:183], v[50:65]
	ds_read_b128 v[232:235], v253 offset:32768
	v_mfma_f32_32x32x16_bf16 v[98:113], v[172:175], v[184:187], v[98:113]
	ds_read_b128 v[228:231], v252 offset:4096
	v_mfma_f32_32x32x16_bf16 v[34:49], v[176:179], v[184:187], v[34:49]
	ds_read_b128 v[236:239], v253 offset:36864
	v_mfma_f32_32x32x16_bf16 v[82:97], v[172:175], v[188:191], v[82:97]
	ds_read_b128 v[240:243], v253 offset:40960
	v_mfma_f32_32x32x16_bf16 v[18:33], v[176:179], v[188:191], v[18:33]
	ds_read_b128 v[244:247], v253 offset:45056
	v_mfma_f32_32x32x16_bf16 v[66:81], v[172:175], v[192:195], v[66:81]
	v_mfma_f32_32x32x16_bf16 v[2:17], v[176:179], v[192:195], v[2:17]
	s_add_u32 s28, s28, 0x80
	s_addc_u32 s29, s29, 0
	s_add_i32 s27, s27, 0x10000
	s_branch .Lp6_kloop
.Lp6_klast:
	v_mfma_f32_32x32x16_bf16 v[114:129], v[172:175], v[180:183], v[114:129]
	v_mfma_f32_32x32x16_bf16 v[50:65], v[176:179], v[180:183], v[50:65]
	v_mfma_f32_32x32x16_bf16 v[98:113], v[172:175], v[184:187], v[98:113]
	v_mfma_f32_32x32x16_bf16 v[34:49], v[176:179], v[184:187], v[34:49]
	v_mfma_f32_32x32x16_bf16 v[82:97], v[172:175], v[188:191], v[82:97]
	v_mfma_f32_32x32x16_bf16 v[18:33], v[176:179], v[188:191], v[18:33]
	v_mfma_f32_32x32x16_bf16 v[66:81], v[172:175], v[192:195], v[66:81]
	v_mfma_f32_32x32x16_bf16 v[2:17], v[176:179], v[192:195], v[2:17]
	s_mov_b32 s25, 16
	s_mov_b32 s30, 0x10000

; DI int opaque_tid() { int t = threadIdx.x; asm volatile("" : "+v"(t)); return t; }
; #define GEMM_ISSUE(KT, ST) do { const int k1_ = (KT) << 6; unsigned char* d_ = ldst + (ST) * STAGE; \
;         _Pragma("unroll") for (int j_ = 0; j_ < 4; ++j_) dma16(ap + (size_t)(64 * j_) * lda + k1_, d_ + j_ * 8192); \
;         _Pragma("unroll") for (int j_ = 0; j_ < NBW; ++j_) dma16(bp + bro[j_] + k1_, d_ + BOFF + j_ * 8192); } while (0)
; template <int NBW>
; DI void gemm_mainloop(f32x16 (&acc)[2][NBW], const bf16_t* A, size_t lda, int m0, const bf16_t* Bt, size_t ldb, int n0, int K, unsigned char* lds, bool pre = false, bool only_issue = false) {
;     ...
;     const int t = opaque_tid(), w = t >> 6, lane = t & 63, r = lane & 31, hh = lane >> 5, wm = w >> 1, wn = w & 1;
;     const int drow = w * 8 + (lane >> 3);
;     const int lchunk = (lane & 7) ^ ((drow >> 1) & 7);
;     const bf16_t* ap = A + (size_t)(m0 + drow) * lda + lchunk * 8;
;     const bf16_t* bp = Bt + (size_t)n0 * ldb + lchunk * 8;
;     size_t bro[NBW];
; #pragma unroll
;     for (int j = 0; j < NBW; ++j) {
;         const int rho = 64 * j + drow; const int wnh = rho / (32 * NBW), wi = rho % (32 * NBW);
;         bro[j] = (size_t)(wnh * 32 * NBW + NBW * (wi & 31) + (wi >> 5)) * ldb;
;     }
;     unsigned char* ldst = lds + w * 1024 + lane * 16;
;     ...
;     if (!pre) GEMM_ISSUE(0, 0);
;     if (only_issue) return;
;     __syncthreads();
;     const int nk = K >> 6;
;     const int xr = (r >> 1) & 7;
;     int xo[4];
; #pragma unroll
;     for (int s = 0; s < 4; ++s) xo[s] = ((2 * s + hh) ^ xr) << 4;
;     const int aofs = (wm * 64 + r) * 128;
;     const int bofs = BOFF + (wn * 32 * NBW + r) * 128;
.LBB0_1721:
	v_and_b32_e32 v15, 31, v13
	v_lshlrev_b32_e32 v12, 7, v12
	s_add_i32 s48, s48, s19
	v_lshrrev_b32_e32 v17, 6, v13
	v_and_or_b32 v12, v12, s28, v15
	v_add_u32_e32 v7, s48, v7
	v_lshrrev_b32_e32 v16, 5, v14
	v_lshrrev_b32_e32 v14, 3, v14
	v_lshlrev_b32_e32 v153, 7, v12
	v_add3_u32 v12, v7, v2, s28
	v_lshlrev_b16_e32 v2, 3, v17
	v_or_b32_e32 v7, v2, v14
	v_sub_u16_e32 v2, v7, v3
	v_and_b32_e32 v2, 31, v2
	v_lshl_add_u32 v2, v2, 2, v8
	v_ashrrev_i32_e32 v3, 31, v2
	v_lshlrev_b64 v[2:3], 13, v[2:3]
	v_lshl_add_u64 v[2:3], v[2:3], 0, s[22:23]
	v_lshl_add_u64 v[2:3], v[2:3], 0, v[132:133]
	v_lshl_add_u64 v[136:137], s[2:3], 0, v[2:3]
	v_sub_u16_e32 v2, v7, v4
	v_and_b32_e32 v2, 31, v2
	v_lshl_add_u32 v2, v2, 2, v9
	v_ashrrev_i32_e32 v3, 31, v2
	v_lshlrev_b64 v[2:3], 13, v[2:3]
	v_lshl_add_u64 v[2:3], v[2:3], 0, s[22:23]
	v_lshl_add_u64 v[2:3], v[2:3], 0, v[132:133]
	v_lshl_add_u64 v[138:139], s[2:3], 0, v[2:3]
	v_sub_u16_e32 v2, v7, v5
	v_and_b32_e32 v2, 31, v2
	v_lshl_add_u32 v2, v2, 2, v10
	v_ashrrev_i32_e32 v3, 31, v2
	v_lshlrev_b64 v[2:3], 13, v[2:3]
	v_lshl_add_u64 v[2:3], v[2:3], 0, s[22:23]
	v_lshl_add_u64 v[2:3], v[2:3], 0, v[132:133]
	v_lshrrev_b32_e32 v18, 1, v13
	v_lshl_add_u64 v[140:141], s[2:3], 0, v[2:3]
	v_sub_u16_e32 v2, v7, v6
	v_bfe_u32 v13, v13, 1, 3
	v_bitop3_b32 v19, v16, v18, 7 bitop3:0x78
	v_and_b32_e32 v2, 31, v2
	v_lshlrev_b32_e32 v148, 4, v19
	v_bitop3_b32 v19, v16, v13, 2 bitop3:0x36
	v_lshl_add_u32 v2, v2, 2, v11
	v_lshlrev_b32_e32 v149, 4, v19
	v_bitop3_b32 v19, v16, v13, 4 bitop3:0x36
	v_bitop3_b32 v13, v16, v13, 6 bitop3:0x36
	v_ashrrev_i32_e32 v3, 31, v2
	v_lshlrev_b32_e32 v151, 4, v13
	v_and_or_b32 v13, v18, s34, v15
	v_lshlrev_b64 v[2:3], 13, v[2:3]
	v_lshlrev_b32_e32 v152, 7, v13
	v_ashrrev_i32_e32 v13, 31, v12
	v_lshl_add_u64 v[2:3], v[2:3], 0, s[22:23]
	v_lshlrev_b64 v[12:13], 13, v[12:13]
	v_lshl_add_u64 v[2:3], v[2:3], 0, v[132:133]
	v_or_b32_e32 v12, v12, v132
	v_lshl_add_u64 v[142:143], s[2:3], 0, v[2:3]
	v_mov_b32_e32 v2, 0
	v_lshlrev_b32_e32 v150, 4, v19
	v_lshl_add_u64 v[134:135], s[50:51], 0, v[12:13]
	s_mov_b32 s19, 0
	s_mov_b64 s[22:23], 0
	s_mov_b32 s21, 0x10000
	v_mov_b32_e32 v3, v2
	v_mov_b32_e32 v4, v2
	v_mov_b32_e32 v5, v2
	v_mov_b32_e32 v6, v2
	v_mov_b32_e32 v7, v2
	v_mov_b32_e32 v8, v2
	v_mov_b32_e32 v9, v2
	v_mov_b32_e32 v10, v2
	v_mov_b32_e32 v11, v2
	v_mov_b32_e32 v12, v2
	v_mov_b32_e32 v13, v2
	v_mov_b32_e32 v14, v2
	v_mov_b32_e32 v15, v2
	v_mov_b32_e32 v16, v2
	v_mov_b32_e32 v17, v2
	v_mov_b32_e32 v18, v2
	v_mov_b32_e32 v19, v2
	v_mov_b32_e32 v20, v2
	v_mov_b32_e32 v21, v2
	v_mov_b32_e32 v22, v2
	v_mov_b32_e32 v23, v2
	v_mov_b32_e32 v24, v2
	v_mov_b32_e32 v25, v2
	v_mov_b32_e32 v26, v2
	v_mov_b32_e32 v27, v2
	v_mov_b32_e32 v28, v2
	v_mov_b32_e32 v29, v2
	v_mov_b32_e32 v30, v2
	v_mov_b32_e32 v31, v2
	v_mov_b32_e32 v32, v2
	v_mov_b32_e32 v33, v2
	v_mov_b32_e32 v34, v2
	v_mov_b32_e32 v35, v2
	v_mov_b32_e32 v36, v2
	v_mov_b32_e32 v37, v2
	v_mov_b32_e32 v38, v2
	v_mov_b32_e32 v39, v2
	v_mov_b32_e32 v40, v2
	v_mov_b32_e32 v41, v2
	v_mov_b32_e32 v42, v2
	v_mov_b32_e32 v43, v2
	v_mov_b32_e32 v44, v2
	v_mov_b32_e32 v45, v2
	v_mov_b32_e32 v46, v2
	v_mov_b32_e32 v47, v2
	v_mov_b32_e32 v48, v2
	v_mov_b32_e32 v49, v2
	v_mov_b32_e32 v50, v2
	v_mov_b32_e32 v51, v2
	v_mov_b32_e32 v52, v2
	v_mov_b32_e32 v53, v2
	v_mov_b32_e32 v54, v2
	v_mov_b32_e32 v55, v2
	v_mov_b32_e32 v56, v2
	v_mov_b32_e32 v57, v2
	v_mov_b32_e32 v58, v2
	v_mov_b32_e32 v59, v2
	v_mov_b32_e32 v60, v2
	v_mov_b32_e32 v61, v2
	v_mov_b32_e32 v62, v2
	v_mov_b32_e32 v63, v2
	v_mov_b32_e32 v64, v2
	v_mov_b32_e32 v65, v2
	v_mov_b32_e32 v66, v2
	v_mov_b32_e32 v67, v2
	v_mov_b32_e32 v68, v2
	v_mov_b32_e32 v69, v2
	v_mov_b32_e32 v70, v2
	v_mov_b32_e32 v71, v2
	v_mov_b32_e32 v72, v2
	v_mov_b32_e32 v73, v2
	v_mov_b32_e32 v74, v2
	v_mov_b32_e32 v75, v2
	v_mov_b32_e32 v76, v2
	v_mov_b32_e32 v77, v2
	v_mov_b32_e32 v78, v2
	v_mov_b32_e32 v79, v2
	v_mov_b32_e32 v80, v2
	v_mov_b32_e32 v81, v2
	v_mov_b32_e32 v82, v2
	v_mov_b32_e32 v83, v2
	v_mov_b32_e32 v84, v2
	v_mov_b32_e32 v85, v2
	v_mov_b32_e32 v86, v2
	v_mov_b32_e32 v87, v2
	v_mov_b32_e32 v88, v2
	v_mov_b32_e32 v89, v2
	v_mov_b32_e32 v90, v2
	v_mov_b32_e32 v91, v2
	v_mov_b32_e32 v92, v2
	v_mov_b32_e32 v93, v2
	v_mov_b32_e32 v94, v2
	v_mov_b32_e32 v95, v2
	v_mov_b32_e32 v96, v2
	v_mov_b32_e32 v97, v2
	v_mov_b32_e32 v98, v2
	v_mov_b32_e32 v99, v2
	v_mov_b32_e32 v100, v2
	v_mov_b32_e32 v101, v2
	v_mov_b32_e32 v102, v2
	v_mov_b32_e32 v103, v2
	v_mov_b32_e32 v104, v2
	v_mov_b32_e32 v105, v2
	v_mov_b32_e32 v106, v2
	v_mov_b32_e32 v107, v2
	v_mov_b32_e32 v108, v2
	v_mov_b32_e32 v109, v2
	v_mov_b32_e32 v110, v2
	v_mov_b32_e32 v111, v2
	v_mov_b32_e32 v112, v2
	v_mov_b32_e32 v113, v2
	v_mov_b32_e32 v114, v2
	v_mov_b32_e32 v115, v2
	v_mov_b32_e32 v116, v2
	v_mov_b32_e32 v117, v2
	v_mov_b32_e32 v118, v2
	v_mov_b32_e32 v119, v2
	v_mov_b32_e32 v120, v2
	v_mov_b32_e32 v121, v2
	v_mov_b32_e32 v122, v2
	v_mov_b32_e32 v123, v2
	v_mov_b32_e32 v124, v2
	v_mov_b32_e32 v125, v2
	v_mov_b32_e32 v126, v2
	v_mov_b32_e32 v127, v2
	v_mov_b32_e32 v128, v2
	v_mov_b32_e32 v129, v2
	s_waitcnt vmcnt(0) lgkmcnt(0)
	s_barrier
	v_mov_b32_e32 v132, v152
	v_mov_b32_e32 v154, v153
	s_add_u32 s22, s22, 0x80
	s_addc_u32 s23, s23, 0
	s_add_i32 s21, s21, 0x10000
	v_add_u32_e32 v252, v132, v148
	v_add_u32_e32 v253, v154, v148
	ds_read_b128 v[224:227], v252
	ds_read_b128 v[232:235], v253 offset:32768
	ds_read_b128 v[228:231], v252 offset:4096
	ds_read_b128 v[236:239], v253 offset:36864
	ds_read_b128 v[240:243], v253 offset:40960
	ds_read_b128 v[244:247], v253 offset:45056
; #define MFMA(a, b, c) __builtin_amdgcn_mfma_f32_32x32x16_bf16((a), (b), (c), 0, 0, 0)
; #define GEMM_ISSUE(KT, ST) do { const int k1_ = (KT) << 6; unsigned char* d_ = ldst + (ST) * STAGE; \
;         _Pragma("unroll") for (int j_ = 0; j_ < 4; ++j_) dma16(ap + (size_t)(64 * j_) * lda + k1_, d_ + j_ * 8192); \
;         _Pragma("unroll") for (int j_ = 0; j_ < NBW; ++j_) dma16(bp + bro[j_] + k1_, d_ + BOFF + j_ * 8192); } while (0)
; template <int NBW>
; DI void gemm_mainloop(f32x16 (&acc)[2][NBW], const bf16_t* A, size_t lda, int m0, const bf16_t* Bt, size_t ldb, int n0, int K, unsigned char* lds, bool pre = false, bool only_issue = false) {
;     ...
;     for (int kt = 0; kt < nk; ++kt) {
;         const unsigned char* st = lds + (kt & 1) * STAGE;
; #pragma unroll
;         for (int s = 0; s < 4; ++s) {
;             if (s == 1 && kt + 1 < nk) GEMM_ISSUE(kt + 1, (kt + 1) & 1);
;             bf16x8 a[2], b[NBW];
; #pragma unroll
;             for (int mb = 0; mb < 2; ++mb) a[mb] = *(const bf16x8*)(st + aofs + mb * 4096 + xo[s]);
; #pragma unroll
;             for (int nb = 0; nb < NBW; ++nb) b[nb] = *(const bf16x8*)(st + bofs + nb * 4096 + xo[s]);
; #pragma unroll
;             for (int mb = 0; mb < 2; ++mb)
; #pragma unroll
;                 for (int nb = 0; nb < NBW; ++nb) acc[mb][nb] = MFMA(a[mb], b[nb], acc[mb][nb]);
;         }
;         __syncthreads();
;     }
.Lp7_kloop:
	s_waitcnt lgkmcnt(4)
	v_mfma_f32_32x32x16_bf16 v[114:129], v[224:227], v[232:235], v[114:129]
	v_add_u32_e32 v252, v132, v149
	v_add_u32_e32 v253, v154, v149
	ds_read_b128 v[156:159], v252
	s_waitcnt lgkmcnt(4)
	v_mfma_f32_32x32x16_bf16 v[50:65], v[228:231], v[232:235], v[50:65]
	ds_read_b128 v[164:167], v253 offset:32768
	s_waitcnt lgkmcnt(4)
	v_mfma_f32_32x32x16_bf16 v[98:113], v[224:227], v[236:239], v[98:113]
	ds_read_b128 v[160:163], v252 offset:4096
	v_mfma_f32_32x32x16_bf16 v[34:49], v[228:231], v[236:239], v[34:49]
	ds_read_b128 v[168:171], v253 offset:36864
	s_waitcnt lgkmcnt(5)
	v_mfma_f32_32x32x16_bf16 v[82:97], v[224:227], v[240:243], v[82:97]
	ds_read_b128 v[172:175], v253 offset:40960
	v_mfma_f32_32x32x16_bf16 v[18:33], v[228:231], v[240:243], v[18:33]
	ds_read_b128 v[176:179], v253 offset:45056
	s_waitcnt lgkmcnt(6)
	v_mfma_f32_32x32x16_bf16 v[66:81], v[224:227], v[244:247], v[66:81]
	v_mfma_f32_32x32x16_bf16 v[2:17], v[228:231], v[244:247], v[2:17]
	s_waitcnt lgkmcnt(4)
	v_mfma_f32_32x32x16_bf16 v[114:129], v[156:159], v[164:167], v[114:129]
	v_add_u32_e32 v252, v132, v150
	v_add_u32_e32 v253, v154, v150
	ds_read_b128 v[224:227], v252
	s_waitcnt lgkmcnt(4)
	v_mfma_f32_32x32x16_bf16 v[50:65], v[160:163], v[164:167], v[50:65]
	ds_read_b128 v[232:235], v253 offset:32768
	s_waitcnt lgkmcnt(4)
	v_mfma_f32_32x32x16_bf16 v[98:113], v[156:159], v[168:171], v[98:113]
	ds_read_b128 v[228:231], v252 offset:4096
	v_mfma_f32_32x32x16_bf16 v[34:49], v[160:163], v[168:171], v[34:49]
	ds_read_b128 v[236:239], v253 offset:36864
	s_waitcnt lgkmcnt(5)
	v_mfma_f32_32x32x16_bf16 v[82:97], v[156:159], v[172:175], v[82:97]
	ds_read_b128 v[240:243], v253 offset:40960
	v_mfma_f32_32x32x16_bf16 v[18:33], v[160:163], v[172:175], v[18:33]
	ds_read_b128 v[244:247], v253 offset:45056
	s_waitcnt lgkmcnt(6)
	v_mfma_f32_32x32x16_bf16 v[66:81], v[156:159], v[176:179], v[66:81]
	v_mfma_f32_32x32x16_bf16 v[2:17], v[160:163], v[176:179], v[2:17]
	s_waitcnt lgkmcnt(4)
	v_mfma_f32_32x32x16_bf16 v[114:129], v[224:227], v[232:235], v[114:129]
	v_add_u32_e32 v252, v132, v151
	v_add_u32_e32 v253, v154, v151
	ds_read_b128 v[156:159], v252
	s_waitcnt lgkmcnt(4)
	v_mfma_f32_32x32x16_bf16 v[50:65], v[228:231], v[232:235], v[50:65]
	ds_read_b128 v[164:167], v253 offset:32768
	s_waitcnt lgkmcnt(4)
	v_mfma_f32_32x32x16_bf16 v[98:113], v[224:227], v[236:239], v[98:113]
	ds_read_b128 v[160:163], v252 offset:4096
	v_mfma_f32_32x32x16_bf16 v[34:49], v[228:231], v[236:239], v[34:49]
	ds_read_b128 v[168:171], v253 offset:36864
	s_waitcnt lgkmcnt(5)
	v_mfma_f32_32x32x16_bf16 v[82:97], v[224:227], v[240:243], v[82:97]
	ds_read_b128 v[172:175], v253 offset:40960
	v_mfma_f32_32x32x16_bf16 v[18:33], v[228:231], v[240:243], v[18:33]
	ds_read_b128 v[176:179], v253 offset:45056
	s_waitcnt lgkmcnt(6)
	v_mfma_f32_32x32x16_bf16 v[66:81], v[224:227], v[244:247], v[66:81]
	v_mfma_f32_32x32x16_bf16 v[2:17], v[228:231], v[244:247], v[2:17]
	v_xor_b32_e32 v132, 0x10000, v132
	v_xor_b32_e32 v154, 0x10000, v154
	s_waitcnt vmcnt(0) lgkmcnt(0)
	s_barrier
	s_cmp_eq_u32 s22, 0x2000
	s_cbranch_scc1 .Lp7_klast
	s_cmp_eq_u32 s22, 0x1f80
	s_cbranch_scc1 .Lp7_knodma
	v_mfma_f32_32x32x16_bf16 v[114:129], v[156:159], v[164:167], v[114:129]
	v_add_u32_e32 v252, v132, v148
	v_add_u32_e32 v253, v154, v148
	ds_read_b128 v[224:227], v252
	s_and_b32 s24, s21, 0x10000
	v_add_u32_e32 v250, s24, v147
	v_lshl_add_u64 v[248:249], v[134:135], 0, s[22:23]
	s_nop 0
	v_readfirstlane_b32 s24, v250
	v_lshl_add_u64 v[250:251], v[248:249], 0, s[10:11]
	s_mov_b32 m0, s24
	s_nop 0
	global_load_lds_dwordx4 v[250:251], off
	v_mfma_f32_32x32x16_bf16 v[50:65], v[160:163], v[164:167], v[50:65]
	ds_read_b128 v[232:235], v253 offset:32768
	v_lshl_add_u64 v[250:251], v[248:249], 0, s[12:13]
	s_add_i32 m0, s24, 0x2000
	s_nop 0
	global_load_lds_dwordx4 v[250:251], off
	v_mfma_f32_32x32x16_bf16 v[98:113], v[156:159], v[168:171], v[98:113]
	ds_read_b128 v[228:231], v252 offset:4096
	v_lshl_add_u64 v[250:251], v[248:249], 0, s[14:15]
	s_add_i32 m0, s24, 0x4000
	s_nop 0
	global_load_lds_dwordx4 v[250:251], off
	v_mfma_f32_32x32x16_bf16 v[34:49], v[160:163], v[168:171], v[34:49]
	ds_read_b128 v[236:239], v253 offset:36864
	v_lshl_add_u64 v[250:251], v[248:249], 0, s[16:17]
	s_add_i32 m0, s24, 0x6000
	s_nop 0
	global_load_lds_dwordx4 v[250:251], off
	v_mfma_f32_32x32x16_bf16 v[82:97], v[156:159], v[172:175], v[82:97]
	ds_read_b128 v[240:243], v253 offset:40960
	v_lshl_add_u64 v[250:251], v[136:137], 0, s[22:23]
	s_add_i32 m0, s24, 0x8000
	s_nop 0
	global_load_lds_dwordx4 v[250:251], off
	v_mfma_f32_32x32x16_bf16 v[18:33], v[160:163], v[172:175], v[18:33]
	ds_read_b128 v[244:247], v253 offset:45056
	v_lshl_add_u64 v[250:251], v[138:139], 0, s[22:23]
	s_add_i32 m0, s24, 0xa000
	s_nop 0
	global_load_lds_dwordx4 v[250:251], off
	v_mfma_f32_32x32x16_bf16 v[66:81], v[156:159], v[176:179], v[66:81]
	v_lshl_add_u64 v[250:251], v[140:141], 0, s[22:23]
	s_add_i32 m0, s24, 0xc000
	s_nop 0
	global_load_lds_dwordx4 v[250:251], off
	v_mfma_f32_32x32x16_bf16 v[2:17], v[160:163], v[176:179], v[2:17]
	v_lshl_add_u64 v[250:251], v[142:143], 0, s[22:23]
	s_add_i32 m0, s24, 0xe000
	s_nop 0
	global_load_lds_dwordx4 v[250:251], off
	s_add_u32 s22, s22, 0x80
	s_addc_u32 s23, s23, 0
	s_add_i32 s21, s21, 0x10000
	s_branch .Lp7_kloop
.Lp7_knodma:
	v_mfma_f32_32x32x16_bf16 v[114:129], v[156:159], v[164:167], v[114:129]
	v_add_u32_e32 v252, v132, v148
	v_add_u32_e32 v253, v154, v148
	ds_read_b128 v[224:227], v252
	v_mfma_f32_32x32x16_bf16 v[50:65], v[160:163], v[164:167], v[50:65]
	ds_read_b128 v[232:235], v253 offset:32768
	v_mfma_f32_32x32x16_bf16 v[98:113], v[156:159], v[168:171], v[98:113]
	ds_read_b128 v[228:231], v252 offset:4096
	v_mfma_f32_32x32x16_bf16 v[34:49], v[160:163], v[168:171], v[34:49]
	ds_read_b128 v[236:239], v253 offset:36864
	v_mfma_f32_32x32x16_bf16 v[82:97], v[156:159], v[172:175], v[82:97]
	ds_read_b128 v[240:243], v253 offset:40960
	v_mfma_f32_32x32x16_bf16 v[18:33], v[160:163], v[172:175], v[18:33]
	ds_read_b128 v[244:247], v253 offset:45056
	v_mfma_f32_32x32x16_bf16 v[66:81], v[156:159], v[176:179], v[66:81]
	v_mfma_f32_32x32x16_bf16 v[2:17], v[160:163], v[176:179], v[2:17]
	s_add_u32 s22, s22, 0x80
	s_addc_u32 s23, s23, 0
	s_add_i32 s21, s21, 0x10000
	s_branch .Lp7_kloop
.Lp7_klast:
	v_mfma_f32_32x32x16_bf16 v[114:129], v[156:159], v[164:167], v[114:129]
	v_mfma_f32_32x32x16_bf16 v[50:65], v[160:163], v[164:167], v[50:65]
	v_mfma_f32_32x32x16_bf16 v[98:113], v[156:159], v[168:171], v[98:113]
	v_mfma_f32_32x32x16_bf16 v[34:49], v[160:163], v[168:171], v[34:49]
	v_mfma_f32_32x32x16_bf16 v[82:97], v[156:159], v[172:175], v[82:97]
	v_mfma_f32_32x32x16_bf16 v[18:33], v[160:163], v[172:175], v[18:33]
	v_mfma_f32_32x32x16_bf16 v[66:81], v[156:159], v[176:179], v[66:81]
	v_mfma_f32_32x32x16_bf16 v[2:17], v[160:163], v[176:179], v[2:17]
	s_mov_b32 s19, 64
	s_mov_b32 s24, 0x10000
